# grid barrier replicated release: last XCD leader bumps every per-XCC generation word; non-leaders poll their own XCC word (32 pollers per word)
# speedup vs baseline: 1.0905x; 1.0024x over previous
.Lcgx_267:
	s_or_b64 exec, exec, s[12:13]
	buffer_inv sc1
	v_cvt_f32_u32_e32 v4, v2
	s_waitcnt vmcnt(0)
	v_readfirstlane_b32 s3, v3
	v_sub_u32_e32 v3, 0, v2
	v_rcp_iflag_f32_e32 v4, v4
	v_add_u32_e32 v5, s3, v1
	v_mul_f32_e32 v4, 0x4f7ffffe, v4
	v_cvt_u32_f32_e32 v4, v4
	v_mul_lo_u32 v1, v3, v4
	v_mul_hi_u32 v1, v4, v1
	v_add_u32_e32 v1, v4, v1
	v_mul_hi_u32 v1, v5, v1
	v_mul_lo_u32 v3, v1, v2
	v_sub_u32_e32 v3, v5, v3
	v_add_u32_e32 v4, 1, v1
	v_cmp_ge_u32_e32 vcc, v3, v2
	s_nop 1
	v_cndmask_b32_e32 v1, v1, v4, vcc
	v_sub_u32_e32 v4, v3, v2
	v_cndmask_b32_e32 v3, v3, v4, vcc
	v_add_u32_e32 v4, 1, v1
	v_cmp_ge_u32_e32 vcc, v3, v2
	v_add_u32_e32 v3, 1, v5
	s_nop 0
	v_cndmask_b32_e32 v1, v1, v4, vcc
	v_mul_lo_u32 v4, v2, v1
	v_add_u32_e32 v2, v4, v2
	v_cmp_ne_u32_e32 vcc, v3, v2
	s_and_saveexec_b64 s[10:11], vcc
	s_xor_b64 s[10:11], exec, s[10:11]
	s_cbranch_execz .Lcgx_281
	s_waitcnt lgkmcnt(0)
	v_mov_b32_e32 v0, 0x2000
	global_load_dword v0, v0, s[8:9] offset:1024 sc1
	s_add_u32 s16, s8, 0x2400
	s_addc_u32 s17, s9, 0
	s_waitcnt vmcnt(0)
	v_cmp_eq_u32_e32 vcc, v0, v1
	s_and_saveexec_b64 s[12:13], vcc
	s_cbranch_execz .Lcgx_280
	s_add_u32 s14, s6, 0x4200
	s_addc_u32 s15, s7, 0
	s_mov_b32 s3, 1
	s_mov_b64 s[18:19], 0
	v_mov_b32_e32 v0, 0
	s_branch .Lcgx_271

.Lcgx_296:
	s_or_b64 exec, exec, s[10:11]
	s_and_saveexec_b64 s[6:7], s[14:15]
	s_cbranch_execz .Lcgx_298
	v_mov_b32_e32 v2, 1
	global_atomic_add v[0:1], v2, off
	s_mov_b32 s16, 0xffffef00
	s_mov_b32 s17, -1
	v_lshl_add_u64 v[4:5], v[0:1], 0, s[16:17]
	global_atomic_add v[4:5], v2, off
	global_atomic_add v[4:5], v2, off offset:256
	global_atomic_add v[4:5], v2, off offset:512
	global_atomic_add v[4:5], v2, off offset:768
	global_atomic_add v[4:5], v2, off offset:1024
	global_atomic_add v[4:5], v2, off offset:1280
	global_atomic_add v[4:5], v2, off offset:1536
	global_atomic_add v[4:5], v2, off offset:1792
	global_atomic_add v[4:5], v2, off offset:2048
	global_atomic_add v[4:5], v2, off offset:2304
	global_atomic_add v[4:5], v2, off offset:2560
	global_atomic_add v[4:5], v2, off offset:2816
	global_atomic_add v[4:5], v2, off offset:3072
	global_atomic_add v[4:5], v2, off offset:3328
	global_atomic_add v[4:5], v2, off offset:3584
	global_atomic_add v[4:5], v2, off offset:3840

.LBB0_322:
	s_waitcnt lgkmcnt(0)
	s_barrier
	v_lshrrev_b32_e32 v140, 6, v154
	v_and_b32_e32 v141, 15, v154
	v_bfe_u32 v142, v154, 4, 2
	v_and_b32_e32 v145, 63, v154
	v_readfirstlane_b32 s4, v140
	s_lshl_b32 s5, s4, 13
	s_add_u32 s6, s44, 0x1e40000
	s_addc_u32 s7, s45, 0
	s_add_u32 s6, s6, s5
	s_addc_u32 s7, s7, 0
	s_add_u32 s8, s6, 0x10000
	s_addc_u32 s9, s7, 0
	s_lshl_b32 s10, s18, 10
	s_lshl_b32 s11, s4, 7
	s_add_u32 s10, s10, s11
	s_add_u32 s10, s10, 0x2300000
	s_add_u32 s10, s44, s10
	s_addc_u32 s11, s45, 0
	s_add_u32 s12, s10, 0x1000000
	s_addc_u32 s13, s11, 0
	s_lshl_b32 s14, s3, 11
	s_lshl_b32 s15, s4, 8
	s_add_u32 s14, s14, s15
	s_add_u32 s14, s14, 0xfc00000
	s_add_u32 s14, s44, s14
	s_addc_u32 s15, s45, 0
	s_add_u32 s16, s14, 0x80000
	s_addc_u32 s17, s15, 0
	s_mov_b32 s94, 0xffff0000
	s_mov_b32 s95, -1
	s_mov_b32 s96, 0
	s_mov_b32 s97, -1
	s_mov_b32 s98, 0
	s_mov_b32 s99, 0xffff0000
	s_lshl_b32 s19, s4, 13
	s_add_u32 s19, s19, 0x10400
	s_cmp_lt_u32 s4, 4
	s_cselect_b32 s5, 0, 0x2a00
	s_add_u32 s19, s19, s5
	v_lshlrev_b32_e32 v143, 7, v141
	v_lshl_or_b32 v143, v142, 4, v143
	v_add_u32_e32 v144, 0x1000, v143
	global_load_dwordx4 v[32:35], v143, s[6:7]
	global_load_dwordx4 v[36:39], v143, s[6:7] offset:64
	global_load_dwordx4 v[40:43], v143, s[6:7] offset:2048
	global_load_dwordx4 v[44:47], v143, s[6:7] offset:2112
	global_load_dwordx4 v[52:55], v144, s[6:7]
	global_load_dwordx4 v[56:59], v144, s[6:7] offset:64
	global_load_dwordx4 v[60:63], v144, s[6:7] offset:2048
	global_load_dwordx4 v[252:255], v144, s[6:7] offset:2112
	global_load_dwordx4 v[220:223], v143, s[8:9]
	global_load_dwordx4 v[224:227], v143, s[8:9] offset:64
	global_load_dwordx4 v[228:231], v143, s[8:9] offset:2048
	global_load_dwordx4 v[232:235], v143, s[8:9] offset:2112
	global_load_dwordx4 v[236:239], v144, s[8:9]
	global_load_dwordx4 v[240:243], v144, s[8:9] offset:64
	global_load_dwordx4 v[244:247], v144, s[8:9] offset:2048
	global_load_dwordx4 v[248:251], v144, s[8:9] offset:2112
	s_lshl_b32 s5, s4, 7
	v_lshrrev_b32_e32 v148, 2, v141
	v_and_b32_e32 v149, 3, v141
	v_lshl_or_b32 v148, v148, 4, v149
	v_mul_u32_u24_e32 v146, 0x410, v148
	v_lshl_add_u32 v146, v142, 4, v146
	v_add_u32_e32 v146, s5, v146
	ds_read_b128 v[0:3], v146
	ds_read_b128 v[4:7], v146 offset:64
	ds_read_b128 v[8:11], v146 offset:4160
	ds_read_b128 v[12:15], v146 offset:4224
	ds_read_b128 v[16:19], v146 offset:8320
	ds_read_b128 v[20:23], v146 offset:8384
	ds_read_b128 v[24:27], v146 offset:12480
	ds_read_b128 v[28:31], v146 offset:12544
	v_mul_u32_u24_e32 v147, 0x4100, v142
	v_lshl_add_u32 v147, v141, 1, v147
	v_add_u32_e32 v147, s5, v147
	s_lshl_b32 s5, s4, 8
	v_lshl_add_u32 v140, v141, 2, s5
	v_add_u32_e32 v140, 0x19600, v140
	ds_read_b32 v132, v140 offset:0
	ds_read_b32 v128, v140 offset:2048
	ds_read_b32 v136, v140 offset:4096
	ds_read_b32 v133, v140 offset:64
	ds_read_b32 v129, v140 offset:2112
	ds_read_b32 v137, v140 offset:4160
	ds_read_b32 v134, v140 offset:128
	ds_read_b32 v130, v140 offset:2176
	ds_read_b32 v138, v140 offset:4224
	ds_read_b32 v135, v140 offset:192
	ds_read_b32 v131, v140 offset:2240
	ds_read_b32 v139, v140 offset:4288
	s_waitcnt vmcnt(8) lgkmcnt(0)
	s_mov_b32 s100, 0xbfb8aa3b
	v_mul_f32_e32 v128, 0xbfb8aa3b, v128
	v_mul_f32_e32 v136, 0xbfb8aa3b, v136
	v_mul_f32_e32 v132, 0x4138aa3b, v132
	v_mul_f32_e32 v129, 0xbfb8aa3b, v129
	v_mul_f32_e32 v137, 0xbfb8aa3b, v137
	v_mul_f32_e32 v133, 0x4138aa3b, v133
	v_mul_f32_e32 v130, 0xbfb8aa3b, v130
	v_mul_f32_e32 v138, 0xbfb8aa3b, v138
	v_mul_f32_e32 v134, 0x4138aa3b, v134
	v_mul_f32_e32 v131, 0xbfb8aa3b, v131
	v_mul_f32_e32 v139, 0xbfb8aa3b, v139
	v_mul_f32_e32 v135, 0x4138aa3b, v135
	v_mfma_f32_16x16x32_bf16 v[64:67], v[0:3], v[32:35], 0
	v_mfma_f32_16x16x32_bf16 v[80:83], v[0:3], v[40:43], 0
	v_mfma_f32_16x16x32_bf16 v[96:99], v[0:3], v[52:55], 0
	v_mfma_f32_16x16x32_bf16 v[112:115], v[0:3], v[60:63], 0
	v_mfma_f32_16x16x32_bf16 v[68:71], v[8:11], v[32:35], 0
	v_mfma_f32_16x16x32_bf16 v[84:87], v[8:11], v[40:43], 0
	v_mfma_f32_16x16x32_bf16 v[100:103], v[8:11], v[52:55], 0
	v_mfma_f32_16x16x32_bf16 v[116:119], v[8:11], v[60:63], 0
	v_mfma_f32_16x16x32_bf16 v[72:75], v[16:19], v[32:35], 0
	v_mfma_f32_16x16x32_bf16 v[88:91], v[16:19], v[40:43], 0
	v_mfma_f32_16x16x32_bf16 v[104:107], v[16:19], v[52:55], 0
	v_mfma_f32_16x16x32_bf16 v[120:123], v[16:19], v[60:63], 0
	v_mfma_f32_16x16x32_bf16 v[76:79], v[24:27], v[32:35], 0
	v_mfma_f32_16x16x32_bf16 v[92:95], v[24:27], v[40:43], 0
	v_mfma_f32_16x16x32_bf16 v[108:111], v[24:27], v[52:55], 0
	v_mfma_f32_16x16x32_bf16 v[124:127], v[24:27], v[60:63], 0
	v_mfma_f32_16x16x32_bf16 v[64:67], v[4:7], v[36:39], v[64:67]
	v_mfma_f32_16x16x32_bf16 v[80:83], v[4:7], v[44:47], v[80:83]
	v_mfma_f32_16x16x32_bf16 v[96:99], v[4:7], v[56:59], v[96:99]
	v_mfma_f32_16x16x32_bf16 v[112:115], v[4:7], v[252:255], v[112:115]
	v_mfma_f32_16x16x32_bf16 v[68:71], v[12:15], v[36:39], v[68:71]
	v_mfma_f32_16x16x32_bf16 v[84:87], v[12:15], v[44:47], v[84:87]
	v_mfma_f32_16x16x32_bf16 v[100:103], v[12:15], v[56:59], v[100:103]
	v_mfma_f32_16x16x32_bf16 v[116:119], v[12:15], v[252:255], v[116:119]
	v_mfma_f32_16x16x32_bf16 v[72:75], v[20:23], v[36:39], v[72:75]
	v_mfma_f32_16x16x32_bf16 v[88:91], v[20:23], v[44:47], v[88:91]
	v_mfma_f32_16x16x32_bf16 v[104:107], v[20:23], v[56:59], v[104:107]
	v_mfma_f32_16x16x32_bf16 v[120:123], v[20:23], v[252:255], v[120:123]
	v_mfma_f32_16x16x32_bf16 v[76:79], v[28:31], v[36:39], v[76:79]
	v_mfma_f32_16x16x32_bf16 v[92:95], v[28:31], v[44:47], v[92:95]
	v_mfma_f32_16x16x32_bf16 v[108:111], v[28:31], v[56:59], v[108:111]
	v_mfma_f32_16x16x32_bf16 v[124:127], v[28:31], v[252:255], v[124:127]
	s_waitcnt vmcnt(0)
	v_mfma_f32_16x16x32_bf16 v[156:159], v[0:3], v[220:223], 0
	v_mfma_f32_16x16x32_bf16 v[172:175], v[0:3], v[228:231], 0
	v_mfma_f32_16x16x32_bf16 v[188:191], v[0:3], v[236:239], 0
	v_mfma_f32_16x16x32_bf16 v[204:207], v[0:3], v[244:247], 0
	v_mfma_f32_16x16x32_bf16 v[160:163], v[8:11], v[220:223], 0
	v_mfma_f32_16x16x32_bf16 v[176:179], v[8:11], v[228:231], 0
	v_mfma_f32_16x16x32_bf16 v[192:195], v[8:11], v[236:239], 0
	v_mfma_f32_16x16x32_bf16 v[208:211], v[8:11], v[244:247], 0
	v_mfma_f32_16x16x32_bf16 v[164:167], v[16:19], v[220:223], 0
	v_mfma_f32_16x16x32_bf16 v[180:183], v[16:19], v[228:231], 0
	v_mfma_f32_16x16x32_bf16 v[196:199], v[16:19], v[236:239], 0
	v_mfma_f32_16x16x32_bf16 v[212:215], v[16:19], v[244:247], 0
	v_mfma_f32_16x16x32_bf16 v[168:171], v[24:27], v[220:223], 0
	v_mfma_f32_16x16x32_bf16 v[184:187], v[24:27], v[228:231], 0
	v_mfma_f32_16x16x32_bf16 v[200:203], v[24:27], v[236:239], 0
	v_mfma_f32_16x16x32_bf16 v[216:219], v[24:27], v[244:247], 0
	v_mfma_f32_16x16x32_bf16 v[156:159], v[4:7], v[224:227], v[156:159]
	v_mfma_f32_16x16x32_bf16 v[172:175], v[4:7], v[232:235], v[172:175]
	v_mfma_f32_16x16x32_bf16 v[188:191], v[4:7], v[240:243], v[188:191]
	v_mfma_f32_16x16x32_bf16 v[204:207], v[4:7], v[248:251], v[204:207]
	v_mfma_f32_16x16x32_bf16 v[160:163], v[12:15], v[224:227], v[160:163]
	v_mfma_f32_16x16x32_bf16 v[176:179], v[12:15], v[232:235], v[176:179]
	v_mfma_f32_16x16x32_bf16 v[192:195], v[12:15], v[240:243], v[192:195]
	v_mfma_f32_16x16x32_bf16 v[208:211], v[12:15], v[248:251], v[208:211]
	v_mfma_f32_16x16x32_bf16 v[164:167], v[20:23], v[224:227], v[164:167]
	v_mfma_f32_16x16x32_bf16 v[180:183], v[20:23], v[232:235], v[180:183]
	v_mfma_f32_16x16x32_bf16 v[196:199], v[20:23], v[240:243], v[196:199]
	v_mfma_f32_16x16x32_bf16 v[212:215], v[20:23], v[248:251], v[212:215]
	v_mfma_f32_16x16x32_bf16 v[168:171], v[28:31], v[224:227], v[168:171]
	v_mfma_f32_16x16x32_bf16 v[184:187], v[28:31], v[232:235], v[184:187]
	v_mfma_f32_16x16x32_bf16 v[200:203], v[28:31], v[240:243], v[200:203]
	v_mfma_f32_16x16x32_bf16 v[216:219], v[28:31], v[248:251], v[216:219]
	v_lshlrev_b32_e32 v220, 11, v142
	v_lshl_add_u32 v220, v141, 1, v220
	v_add_u32_e32 v220, s19, v220
	v_lshrrev_b32_e32 v148, 3, v145
	v_and_b32_e32 v149, 7, v145
	v_mul_u32_u24_e32 v221, 0x410, v148
	v_lshl_add_u32 v221, v149, 4, v221
	s_lshl_b32 s5, s4, 7
	v_add_u32_e32 v221, s5, v221
	v_lshlrev_b32_e32 v222, 7, v148
	v_lshl_add_u32 v222, v149, 4, v222
	v_add_u32_e32 v222, s19, v222
	v_lshlrev_b32_e32 v223, 10, v148
	v_lshl_add_u32 v223, v149, 4, v223
	v_lshlrev_b32_e32 v224, 2, v141
	v_add_u32_e32 v225, 48, v145
	v_and_b32_e32 v225, 63, v225
	v_lshlrev_b32_e32 v225, 2, v225
	v_add_u32_e32 v226, 32, v145
	v_and_b32_e32 v226, 63, v226
	v_lshlrev_b32_e32 v226, 2, v226
	v_add_u32_e32 v227, 16, v145
	v_and_b32_e32 v227, 63, v227
	v_lshlrev_b32_e32 v227, 2, v227
	ds_read_u16 v32, v147 offset:0
	ds_read_u16 v33, v147 offset:1040
	ds_read_u16 v34, v147 offset:2080
	ds_read_u16 v35, v147 offset:3120
	ds_read_u16 v36, v147 offset:4160
	ds_read_u16 v37, v147 offset:5200
	ds_read_u16 v38, v147 offset:6240
	ds_read_u16 v39, v147 offset:7280
	ds_read_u16 v40, v147 offset:8320
	ds_read_u16 v41, v147 offset:9360
	ds_read_u16 v42, v147 offset:10400
	ds_read_u16 v43, v147 offset:11440
	ds_read_u16 v44, v147 offset:12480
	ds_read_u16 v45, v147 offset:13520
	ds_read_u16 v46, v147 offset:14560
	ds_read_u16 v47, v147 offset:15600
	ds_read_u16 v52, v147 offset:32
	ds_read_u16 v53, v147 offset:1072
	ds_read_u16 v54, v147 offset:2112
	ds_read_u16 v55, v147 offset:3152
	ds_read_u16 v56, v147 offset:4192
	ds_read_u16 v57, v147 offset:5232
	ds_read_u16 v58, v147 offset:6272
	ds_read_u16 v59, v147 offset:7312
	ds_read_u16 v60, v147 offset:8352
	ds_read_u16 v61, v147 offset:9392
	ds_read_u16 v62, v147 offset:10432
	ds_read_u16 v63, v147 offset:11472
	ds_read_u16 v252, v147 offset:12512
	ds_read_u16 v253, v147 offset:13552
	ds_read_u16 v254, v147 offset:14592
	ds_read_u16 v255, v147 offset:15632
	v_fma_f32 v64, v64, s100, v128
	v_fma_f32 v65, v65, s100, v128
	v_fma_f32 v66, v66, s100, v128
	v_fma_f32 v67, v67, s100, v128
	v_fma_f32 v68, v68, s100, v128
	v_fma_f32 v69, v69, s100, v128
	v_fma_f32 v70, v70, s100, v128
	v_fma_f32 v71, v71, s100, v128
	v_exp_f32_e32 v64, v64
	v_exp_f32_e32 v65, v65
	v_exp_f32_e32 v66, v66
	v_exp_f32_e32 v67, v67
	v_exp_f32_e32 v68, v68
	v_exp_f32_e32 v69, v69
	v_exp_f32_e32 v70, v70
	v_exp_f32_e32 v71, v71
	v_add_f32_e32 v64, 1.0, v64
	v_add_f32_e32 v65, 1.0, v65
	v_add_f32_e32 v66, 1.0, v66
	v_add_f32_e32 v67, 1.0, v67
	v_add_f32_e32 v68, 1.0, v68
	v_add_f32_e32 v69, 1.0, v69
	v_add_f32_e32 v70, 1.0, v70
	v_add_f32_e32 v71, 1.0, v71
	v_rcp_f32_e32 v64, v64
	v_rcp_f32_e32 v65, v65
	v_rcp_f32_e32 v66, v66
	v_rcp_f32_e32 v67, v67
	v_rcp_f32_e32 v68, v68
	v_rcp_f32_e32 v69, v69
	v_rcp_f32_e32 v70, v70
	v_rcp_f32_e32 v71, v71
	v_mul_f32_e32 v64, v64, v132
	v_mul_f32_e32 v65, v65, v132
	v_mul_f32_e32 v66, v66, v132
	v_mul_f32_e32 v67, v67, v132
	v_mul_f32_e32 v68, v68, v132
	v_mul_f32_e32 v69, v69, v132
	v_mul_f32_e32 v70, v70, v132
	v_mul_f32_e32 v71, v71, v132
	v_exp_f32_e32 v64, v64
	v_exp_f32_e32 v65, v65
	v_exp_f32_e32 v66, v66
	v_exp_f32_e32 v67, v67
	v_exp_f32_e32 v68, v68
	v_exp_f32_e32 v69, v69
	v_exp_f32_e32 v70, v70
	v_exp_f32_e32 v71, v71
	v_fma_f32 v72, v72, s100, v128
	v_fma_f32 v73, v73, s100, v128
	v_fma_f32 v74, v74, s100, v128
	v_fma_f32 v75, v75, s100, v128
	v_fma_f32 v76, v76, s100, v128
	v_fma_f32 v77, v77, s100, v128
	v_fma_f32 v78, v78, s100, v128
	v_fma_f32 v79, v79, s100, v128
	v_exp_f32_e32 v72, v72
	v_exp_f32_e32 v73, v73
	v_exp_f32_e32 v74, v74
	v_exp_f32_e32 v75, v75
	v_exp_f32_e32 v76, v76
	v_exp_f32_e32 v77, v77
	v_exp_f32_e32 v78, v78
	v_exp_f32_e32 v79, v79
	v_add_f32_e32 v72, 1.0, v72
	v_add_f32_e32 v73, 1.0, v73
	v_add_f32_e32 v74, 1.0, v74
	v_add_f32_e32 v75, 1.0, v75
	v_add_f32_e32 v76, 1.0, v76
	v_add_f32_e32 v77, 1.0, v77
	v_add_f32_e32 v78, 1.0, v78
	v_add_f32_e32 v79, 1.0, v79
	v_rcp_f32_e32 v72, v72
	v_rcp_f32_e32 v73, v73
	v_rcp_f32_e32 v74, v74
	v_rcp_f32_e32 v75, v75
	v_rcp_f32_e32 v76, v76
	v_rcp_f32_e32 v77, v77
	v_rcp_f32_e32 v78, v78
	v_rcp_f32_e32 v79, v79
	v_mul_f32_e32 v72, v72, v132
	v_mul_f32_e32 v73, v73, v132
	v_mul_f32_e32 v74, v74, v132
	v_mul_f32_e32 v75, v75, v132
	v_mul_f32_e32 v76, v76, v132
	v_mul_f32_e32 v77, v77, v132
	v_mul_f32_e32 v78, v78, v132
	v_mul_f32_e32 v79, v79, v132
	v_exp_f32_e32 v72, v72
	v_exp_f32_e32 v73, v73
	v_exp_f32_e32 v74, v74
	v_exp_f32_e32 v75, v75
	v_exp_f32_e32 v76, v76
	v_exp_f32_e32 v77, v77
	v_exp_f32_e32 v78, v78
	v_exp_f32_e32 v79, v79
	v_fma_f32 v80, v80, s100, v129
	v_fma_f32 v81, v81, s100, v129
	v_fma_f32 v82, v82, s100, v129
	v_fma_f32 v83, v83, s100, v129
	v_fma_f32 v84, v84, s100, v129
	v_fma_f32 v85, v85, s100, v129
	v_fma_f32 v86, v86, s100, v129
	v_fma_f32 v87, v87, s100, v129
	v_exp_f32_e32 v80, v80
	v_exp_f32_e32 v81, v81
	v_exp_f32_e32 v82, v82
	v_exp_f32_e32 v83, v83
	v_exp_f32_e32 v84, v84
	v_exp_f32_e32 v85, v85
	v_exp_f32_e32 v86, v86
	v_exp_f32_e32 v87, v87
	v_add_f32_e32 v80, 1.0, v80
	v_add_f32_e32 v81, 1.0, v81
	v_add_f32_e32 v82, 1.0, v82
	v_add_f32_e32 v83, 1.0, v83
	v_add_f32_e32 v84, 1.0, v84
	v_add_f32_e32 v85, 1.0, v85
	v_add_f32_e32 v86, 1.0, v86
	v_add_f32_e32 v87, 1.0, v87
	v_rcp_f32_e32 v80, v80
	v_rcp_f32_e32 v81, v81
	v_rcp_f32_e32 v82, v82
	v_rcp_f32_e32 v83, v83
	v_rcp_f32_e32 v84, v84
	v_rcp_f32_e32 v85, v85
	v_rcp_f32_e32 v86, v86
	v_rcp_f32_e32 v87, v87
	v_mul_f32_e32 v80, v80, v133
	v_mul_f32_e32 v81, v81, v133
	v_mul_f32_e32 v82, v82, v133
	v_mul_f32_e32 v83, v83, v133
	v_mul_f32_e32 v84, v84, v133
	v_mul_f32_e32 v85, v85, v133
	v_mul_f32_e32 v86, v86, v133
	v_mul_f32_e32 v87, v87, v133
	v_exp_f32_e32 v80, v80
	v_exp_f32_e32 v81, v81
	v_exp_f32_e32 v82, v82
	v_exp_f32_e32 v83, v83
	v_exp_f32_e32 v84, v84
	v_exp_f32_e32 v85, v85
	v_exp_f32_e32 v86, v86
	v_exp_f32_e32 v87, v87
	v_fma_f32 v88, v88, s100, v129
	v_fma_f32 v89, v89, s100, v129
	v_fma_f32 v90, v90, s100, v129
	v_fma_f32 v91, v91, s100, v129
	v_fma_f32 v92, v92, s100, v129
	v_fma_f32 v93, v93, s100, v129
	v_fma_f32 v94, v94, s100, v129
	v_fma_f32 v95, v95, s100, v129
	v_exp_f32_e32 v88, v88
	v_exp_f32_e32 v89, v89
	v_exp_f32_e32 v90, v90
	v_exp_f32_e32 v91, v91
	v_exp_f32_e32 v92, v92
	v_exp_f32_e32 v93, v93
	v_exp_f32_e32 v94, v94
	v_exp_f32_e32 v95, v95
	v_add_f32_e32 v88, 1.0, v88
	v_add_f32_e32 v89, 1.0, v89
	v_add_f32_e32 v90, 1.0, v90
	v_add_f32_e32 v91, 1.0, v91
	v_add_f32_e32 v92, 1.0, v92
	v_add_f32_e32 v93, 1.0, v93
	v_add_f32_e32 v94, 1.0, v94
	v_add_f32_e32 v95, 1.0, v95
	v_rcp_f32_e32 v88, v88
	v_rcp_f32_e32 v89, v89
	v_rcp_f32_e32 v90, v90
	v_rcp_f32_e32 v91, v91
	v_rcp_f32_e32 v92, v92
	v_rcp_f32_e32 v93, v93
	v_rcp_f32_e32 v94, v94
	v_rcp_f32_e32 v95, v95
	v_mul_f32_e32 v88, v88, v133
	v_mul_f32_e32 v89, v89, v133
	v_mul_f32_e32 v90, v90, v133
	v_mul_f32_e32 v91, v91, v133
	v_mul_f32_e32 v92, v92, v133
	v_mul_f32_e32 v93, v93, v133
	v_mul_f32_e32 v94, v94, v133
	v_mul_f32_e32 v95, v95, v133
	v_exp_f32_e32 v88, v88
	v_exp_f32_e32 v89, v89
	v_exp_f32_e32 v90, v90
	v_exp_f32_e32 v91, v91
	v_exp_f32_e32 v92, v92
	v_exp_f32_e32 v93, v93
	v_exp_f32_e32 v94, v94
	v_exp_f32_e32 v95, v95
	v_fma_f32 v96, v96, s100, v130
	v_fma_f32 v97, v97, s100, v130
	v_fma_f32 v98, v98, s100, v130
	v_fma_f32 v99, v99, s100, v130
	v_fma_f32 v100, v100, s100, v130
	v_fma_f32 v101, v101, s100, v130
	v_fma_f32 v102, v102, s100, v130
	v_fma_f32 v103, v103, s100, v130
	v_exp_f32_e32 v96, v96
	v_exp_f32_e32 v97, v97
	v_exp_f32_e32 v98, v98
	v_exp_f32_e32 v99, v99
	v_exp_f32_e32 v100, v100
	v_exp_f32_e32 v101, v101
	v_exp_f32_e32 v102, v102
	v_exp_f32_e32 v103, v103
	v_add_f32_e32 v96, 1.0, v96
	v_add_f32_e32 v97, 1.0, v97
	v_add_f32_e32 v98, 1.0, v98
	v_add_f32_e32 v99, 1.0, v99
	v_add_f32_e32 v100, 1.0, v100
	v_add_f32_e32 v101, 1.0, v101
	v_add_f32_e32 v102, 1.0, v102
	v_add_f32_e32 v103, 1.0, v103
	v_rcp_f32_e32 v96, v96
	v_rcp_f32_e32 v97, v97
	v_rcp_f32_e32 v98, v98
	v_rcp_f32_e32 v99, v99
	v_rcp_f32_e32 v100, v100
	v_rcp_f32_e32 v101, v101
	v_rcp_f32_e32 v102, v102
	v_rcp_f32_e32 v103, v103
	v_mul_f32_e32 v96, v96, v134
	v_mul_f32_e32 v97, v97, v134
	v_mul_f32_e32 v98, v98, v134
	v_mul_f32_e32 v99, v99, v134
	v_mul_f32_e32 v100, v100, v134
	v_mul_f32_e32 v101, v101, v134
	v_mul_f32_e32 v102, v102, v134
	v_mul_f32_e32 v103, v103, v134
	v_exp_f32_e32 v96, v96
	v_exp_f32_e32 v97, v97
	v_exp_f32_e32 v98, v98
	v_exp_f32_e32 v99, v99
	v_exp_f32_e32 v100, v100
	v_exp_f32_e32 v101, v101
	v_exp_f32_e32 v102, v102
	v_exp_f32_e32 v103, v103
	v_fma_f32 v104, v104, s100, v130
	v_fma_f32 v105, v105, s100, v130
	v_fma_f32 v106, v106, s100, v130
	v_fma_f32 v107, v107, s100, v130
	v_fma_f32 v108, v108, s100, v130
	v_fma_f32 v109, v109, s100, v130
	v_fma_f32 v110, v110, s100, v130
	v_fma_f32 v111, v111, s100, v130
	v_exp_f32_e32 v104, v104
	v_exp_f32_e32 v105, v105
	v_exp_f32_e32 v106, v106
	v_exp_f32_e32 v107, v107
	v_exp_f32_e32 v108, v108
	v_exp_f32_e32 v109, v109
	v_exp_f32_e32 v110, v110
	v_exp_f32_e32 v111, v111
	v_add_f32_e32 v104, 1.0, v104
	v_add_f32_e32 v105, 1.0, v105
	v_add_f32_e32 v106, 1.0, v106
	v_add_f32_e32 v107, 1.0, v107
	v_add_f32_e32 v108, 1.0, v108
	v_add_f32_e32 v109, 1.0, v109
	v_add_f32_e32 v110, 1.0, v110
	v_add_f32_e32 v111, 1.0, v111
	v_rcp_f32_e32 v104, v104
	v_rcp_f32_e32 v105, v105
	v_rcp_f32_e32 v106, v106
	v_rcp_f32_e32 v107, v107
	v_rcp_f32_e32 v108, v108
	v_rcp_f32_e32 v109, v109
	v_rcp_f32_e32 v110, v110
	v_rcp_f32_e32 v111, v111
	v_mul_f32_e32 v104, v104, v134
	v_mul_f32_e32 v105, v105, v134
	v_mul_f32_e32 v106, v106, v134
	v_mul_f32_e32 v107, v107, v134
	v_mul_f32_e32 v108, v108, v134
	v_mul_f32_e32 v109, v109, v134
	v_mul_f32_e32 v110, v110, v134
	v_mul_f32_e32 v111, v111, v134
	v_exp_f32_e32 v104, v104
	v_exp_f32_e32 v105, v105
	v_exp_f32_e32 v106, v106
	v_exp_f32_e32 v107, v107
	v_exp_f32_e32 v108, v108
	v_exp_f32_e32 v109, v109
	v_exp_f32_e32 v110, v110
	v_exp_f32_e32 v111, v111
	v_fma_f32 v112, v112, s100, v131
	v_fma_f32 v113, v113, s100, v131
	v_fma_f32 v114, v114, s100, v131
	v_fma_f32 v115, v115, s100, v131
	v_fma_f32 v116, v116, s100, v131
	v_fma_f32 v117, v117, s100, v131
	v_fma_f32 v118, v118, s100, v131
	v_fma_f32 v119, v119, s100, v131
	v_exp_f32_e32 v112, v112
	v_exp_f32_e32 v113, v113
	v_exp_f32_e32 v114, v114
	v_exp_f32_e32 v115, v115
	v_exp_f32_e32 v116, v116
	v_exp_f32_e32 v117, v117
	v_exp_f32_e32 v118, v118
	v_exp_f32_e32 v119, v119
	v_add_f32_e32 v112, 1.0, v112
	v_add_f32_e32 v113, 1.0, v113
	v_add_f32_e32 v114, 1.0, v114
	v_add_f32_e32 v115, 1.0, v115
	v_add_f32_e32 v116, 1.0, v116
	v_add_f32_e32 v117, 1.0, v117
	v_add_f32_e32 v118, 1.0, v118
	v_add_f32_e32 v119, 1.0, v119
	v_rcp_f32_e32 v112, v112
	v_rcp_f32_e32 v113, v113
	v_rcp_f32_e32 v114, v114
	v_rcp_f32_e32 v115, v115
	v_rcp_f32_e32 v116, v116
	v_rcp_f32_e32 v117, v117
	v_rcp_f32_e32 v118, v118
	v_rcp_f32_e32 v119, v119
	v_mul_f32_e32 v112, v112, v135
	v_mul_f32_e32 v113, v113, v135
	v_mul_f32_e32 v114, v114, v135
	v_mul_f32_e32 v115, v115, v135
	v_mul_f32_e32 v116, v116, v135
	v_mul_f32_e32 v117, v117, v135
	v_mul_f32_e32 v118, v118, v135
	v_mul_f32_e32 v119, v119, v135
	v_exp_f32_e32 v112, v112
	v_exp_f32_e32 v113, v113
	v_exp_f32_e32 v114, v114
	v_exp_f32_e32 v115, v115
	v_exp_f32_e32 v116, v116
	v_exp_f32_e32 v117, v117
	v_exp_f32_e32 v118, v118
	v_exp_f32_e32 v119, v119
	v_fma_f32 v120, v120, s100, v131
	v_fma_f32 v121, v121, s100, v131
	v_fma_f32 v122, v122, s100, v131
	v_fma_f32 v123, v123, s100, v131
	v_fma_f32 v124, v124, s100, v131
	v_fma_f32 v125, v125, s100, v131
	v_fma_f32 v126, v126, s100, v131
	v_fma_f32 v127, v127, s100, v131
	v_exp_f32_e32 v120, v120
	v_exp_f32_e32 v121, v121
	v_exp_f32_e32 v122, v122
	v_exp_f32_e32 v123, v123
	v_exp_f32_e32 v124, v124
	v_exp_f32_e32 v125, v125
	v_exp_f32_e32 v126, v126
	v_exp_f32_e32 v127, v127
	v_add_f32_e32 v120, 1.0, v120
	v_add_f32_e32 v121, 1.0, v121
	v_add_f32_e32 v122, 1.0, v122
	v_add_f32_e32 v123, 1.0, v123
	v_add_f32_e32 v124, 1.0, v124
	v_add_f32_e32 v125, 1.0, v125
	v_add_f32_e32 v126, 1.0, v126
	v_add_f32_e32 v127, 1.0, v127
	v_rcp_f32_e32 v120, v120
	v_rcp_f32_e32 v121, v121
	v_rcp_f32_e32 v122, v122
	v_rcp_f32_e32 v123, v123
	v_rcp_f32_e32 v124, v124
	v_rcp_f32_e32 v125, v125
	v_rcp_f32_e32 v126, v126
	v_rcp_f32_e32 v127, v127
	v_mul_f32_e32 v120, v120, v135
	v_mul_f32_e32 v121, v121, v135
	v_mul_f32_e32 v122, v122, v135
	v_mul_f32_e32 v123, v123, v135
	v_mul_f32_e32 v124, v124, v135
	v_mul_f32_e32 v125, v125, v135
	v_mul_f32_e32 v126, v126, v135
	v_mul_f32_e32 v127, v127, v135
	v_exp_f32_e32 v120, v120
	v_exp_f32_e32 v121, v121
	v_exp_f32_e32 v122, v122
	v_exp_f32_e32 v123, v123
	v_exp_f32_e32 v124, v124
	v_exp_f32_e32 v125, v125
	v_exp_f32_e32 v126, v126
	v_exp_f32_e32 v127, v127
	ds_read_u16 v0, v147 offset:64
	ds_read_u16 v1, v147 offset:1104
	ds_read_u16 v2, v147 offset:2144
	ds_read_u16 v3, v147 offset:3184
	ds_read_u16 v4, v147 offset:4224
	ds_read_u16 v5, v147 offset:5264
	ds_read_u16 v6, v147 offset:6304
	ds_read_u16 v7, v147 offset:7344
	ds_read_u16 v8, v147 offset:8384
	ds_read_u16 v9, v147 offset:9424
	ds_read_u16 v10, v147 offset:10464
	ds_read_u16 v11, v147 offset:11504
	ds_read_u16 v12, v147 offset:12544
	ds_read_u16 v13, v147 offset:13584
	ds_read_u16 v14, v147 offset:14624
	ds_read_u16 v15, v147 offset:15664
	ds_read_u16 v16, v147 offset:96
	ds_read_u16 v17, v147 offset:1136
	ds_read_u16 v18, v147 offset:2176
	ds_read_u16 v19, v147 offset:3216
	ds_read_u16 v20, v147 offset:4256
	ds_read_u16 v21, v147 offset:5296
	ds_read_u16 v22, v147 offset:6336
	ds_read_u16 v23, v147 offset:7376
	ds_read_u16 v24, v147 offset:8416
	ds_read_u16 v25, v147 offset:9456
	ds_read_u16 v26, v147 offset:10496
	ds_read_u16 v27, v147 offset:11536
	ds_read_u16 v28, v147 offset:12576
	ds_read_u16 v29, v147 offset:13616
	ds_read_u16 v30, v147 offset:14656
	ds_read_u16 v31, v147 offset:15696
	s_waitcnt lgkmcnt(0)
	v_lshlrev_b32_e32 v32, 16, v32
	v_lshlrev_b32_e32 v33, 16, v33
	v_lshlrev_b32_e32 v34, 16, v34
	v_lshlrev_b32_e32 v35, 16, v35
	v_lshlrev_b32_e32 v36, 16, v36
	v_lshlrev_b32_e32 v37, 16, v37
	v_lshlrev_b32_e32 v38, 16, v38
	v_lshlrev_b32_e32 v39, 16, v39
	v_lshlrev_b32_e32 v40, 16, v40
	v_lshlrev_b32_e32 v41, 16, v41
	v_lshlrev_b32_e32 v42, 16, v42
	v_lshlrev_b32_e32 v43, 16, v43
	v_lshlrev_b32_e32 v44, 16, v44
	v_lshlrev_b32_e32 v45, 16, v45
	v_lshlrev_b32_e32 v46, 16, v46
	v_lshlrev_b32_e32 v47, 16, v47
	v_lshlrev_b32_e32 v52, 16, v52
	v_lshlrev_b32_e32 v53, 16, v53
	v_lshlrev_b32_e32 v54, 16, v54
	v_lshlrev_b32_e32 v55, 16, v55
	v_lshlrev_b32_e32 v56, 16, v56
	v_lshlrev_b32_e32 v57, 16, v57
	v_lshlrev_b32_e32 v58, 16, v58
	v_lshlrev_b32_e32 v59, 16, v59
	v_lshlrev_b32_e32 v60, 16, v60
	v_lshlrev_b32_e32 v61, 16, v61
	v_lshlrev_b32_e32 v62, 16, v62
	v_lshlrev_b32_e32 v63, 16, v63
	v_lshlrev_b32_e32 v252, 16, v252
	v_lshlrev_b32_e32 v253, 16, v253
	v_lshlrev_b32_e32 v254, 16, v254
	v_lshlrev_b32_e32 v255, 16, v255
	v_lshlrev_b32_e32 v0, 16, v0
	v_lshlrev_b32_e32 v1, 16, v1
	v_lshlrev_b32_e32 v2, 16, v2
	v_lshlrev_b32_e32 v3, 16, v3
	v_lshlrev_b32_e32 v4, 16, v4
	v_lshlrev_b32_e32 v5, 16, v5
	v_lshlrev_b32_e32 v6, 16, v6
	v_lshlrev_b32_e32 v7, 16, v7
	v_lshlrev_b32_e32 v8, 16, v8
	v_lshlrev_b32_e32 v9, 16, v9
	v_lshlrev_b32_e32 v10, 16, v10
	v_lshlrev_b32_e32 v11, 16, v11
	v_lshlrev_b32_e32 v12, 16, v12
	v_lshlrev_b32_e32 v13, 16, v13
	v_lshlrev_b32_e32 v14, 16, v14
	v_lshlrev_b32_e32 v15, 16, v15
	v_lshlrev_b32_e32 v16, 16, v16
	v_lshlrev_b32_e32 v17, 16, v17
	v_lshlrev_b32_e32 v18, 16, v18
	v_lshlrev_b32_e32 v19, 16, v19
	v_lshlrev_b32_e32 v20, 16, v20
	v_lshlrev_b32_e32 v21, 16, v21
	v_lshlrev_b32_e32 v22, 16, v22
	v_lshlrev_b32_e32 v23, 16, v23
	v_lshlrev_b32_e32 v24, 16, v24
	v_lshlrev_b32_e32 v25, 16, v25
	v_lshlrev_b32_e32 v26, 16, v26
	v_lshlrev_b32_e32 v27, 16, v27
	v_lshlrev_b32_e32 v28, 16, v28
	v_lshlrev_b32_e32 v29, 16, v29
	v_lshlrev_b32_e32 v30, 16, v30
	v_lshlrev_b32_e32 v31, 16, v31
	v_fma_f32 v156, v156, s100, v136
	v_fma_f32 v157, v157, s100, v136
	v_fma_f32 v158, v158, s100, v136
	v_fma_f32 v159, v159, s100, v136
	v_exp_f32_e32 v156, v156
	v_exp_f32_e32 v157, v157
	v_exp_f32_e32 v158, v158
	v_exp_f32_e32 v159, v159
	v_fma_f32 v148, -v64, v64, 1.0
	v_fma_f32 v149, -v65, v65, 1.0
	v_fma_f32 v150, -v66, v66, 1.0
	v_fma_f32 v151, -v67, v67, 1.0
	v_add_f32_e32 v156, 1.0, v156
	v_add_f32_e32 v157, 1.0, v157
	v_add_f32_e32 v158, 1.0, v158
	v_add_f32_e32 v159, 1.0, v159
	v_rcp_f32_e32 v156, v156
	v_rcp_f32_e32 v157, v157
	v_rcp_f32_e32 v158, v158
	v_rcp_f32_e32 v159, v159
	v_max_f32_e32 v148, 0, v148
	v_max_f32_e32 v149, 0, v149
	v_max_f32_e32 v150, 0, v150
	v_max_f32_e32 v151, 0, v151
	v_sqrt_f32_e32 v148, v148
	v_sqrt_f32_e32 v149, v149
	v_sqrt_f32_e32 v150, v150
	v_sqrt_f32_e32 v151, v151
	v_mul_f32_e32 v156, v156, v32
	v_mul_f32_e32 v157, v157, v33
	v_mul_f32_e32 v158, v158, v34
	v_mul_f32_e32 v159, v159, v35
	v_mul_f32_e32 v156, v156, v148
	v_mul_f32_e32 v157, v157, v149
	v_mul_f32_e32 v158, v158, v150
	v_mul_f32_e32 v159, v159, v151
	v_fma_f32 v160, v160, s100, v136
	v_fma_f32 v161, v161, s100, v136
	v_fma_f32 v162, v162, s100, v136
	v_fma_f32 v163, v163, s100, v136
	v_exp_f32_e32 v160, v160
	v_exp_f32_e32 v161, v161
	v_exp_f32_e32 v162, v162
	v_exp_f32_e32 v163, v163
	v_fma_f32 v148, -v68, v68, 1.0
	v_fma_f32 v149, -v69, v69, 1.0
	v_fma_f32 v150, -v70, v70, 1.0
	v_fma_f32 v151, -v71, v71, 1.0
	v_add_f32_e32 v160, 1.0, v160
	v_add_f32_e32 v161, 1.0, v161
	v_add_f32_e32 v162, 1.0, v162
	v_add_f32_e32 v163, 1.0, v163
	v_rcp_f32_e32 v160, v160
	v_rcp_f32_e32 v161, v161
	v_rcp_f32_e32 v162, v162
	v_rcp_f32_e32 v163, v163
	v_max_f32_e32 v148, 0, v148
	v_max_f32_e32 v149, 0, v149
	v_max_f32_e32 v150, 0, v150
	v_max_f32_e32 v151, 0, v151
	v_sqrt_f32_e32 v148, v148
	v_sqrt_f32_e32 v149, v149
	v_sqrt_f32_e32 v150, v150
	v_sqrt_f32_e32 v151, v151
	v_mul_f32_e32 v160, v160, v36
	v_mul_f32_e32 v161, v161, v37
	v_mul_f32_e32 v162, v162, v38
	v_mul_f32_e32 v163, v163, v39
	v_mul_f32_e32 v160, v160, v148
	v_mul_f32_e32 v161, v161, v149
	v_mul_f32_e32 v162, v162, v150
	v_mul_f32_e32 v163, v163, v151
	v_fma_f32 v164, v164, s100, v136
	v_fma_f32 v165, v165, s100, v136
	v_fma_f32 v166, v166, s100, v136
	v_fma_f32 v167, v167, s100, v136
	v_exp_f32_e32 v164, v164
	v_exp_f32_e32 v165, v165
	v_exp_f32_e32 v166, v166
	v_exp_f32_e32 v167, v167
	v_fma_f32 v148, -v72, v72, 1.0
	v_fma_f32 v149, -v73, v73, 1.0
	v_fma_f32 v150, -v74, v74, 1.0
	v_fma_f32 v151, -v75, v75, 1.0
	v_add_f32_e32 v164, 1.0, v164
	v_add_f32_e32 v165, 1.0, v165
	v_add_f32_e32 v166, 1.0, v166
	v_add_f32_e32 v167, 1.0, v167
	v_rcp_f32_e32 v164, v164
	v_rcp_f32_e32 v165, v165
	v_rcp_f32_e32 v166, v166
	v_rcp_f32_e32 v167, v167
	v_max_f32_e32 v148, 0, v148
	v_max_f32_e32 v149, 0, v149
	v_max_f32_e32 v150, 0, v150
	v_max_f32_e32 v151, 0, v151
	v_sqrt_f32_e32 v148, v148
	v_sqrt_f32_e32 v149, v149
	v_sqrt_f32_e32 v150, v150
	v_sqrt_f32_e32 v151, v151
	v_mul_f32_e32 v164, v164, v40
	v_mul_f32_e32 v165, v165, v41
	v_mul_f32_e32 v166, v166, v42
	v_mul_f32_e32 v167, v167, v43
	v_mul_f32_e32 v164, v164, v148
	v_mul_f32_e32 v165, v165, v149
	v_mul_f32_e32 v166, v166, v150
	v_mul_f32_e32 v167, v167, v151
	v_fma_f32 v168, v168, s100, v136
	v_fma_f32 v169, v169, s100, v136
	v_fma_f32 v170, v170, s100, v136
	v_fma_f32 v171, v171, s100, v136
	v_exp_f32_e32 v168, v168
	v_exp_f32_e32 v169, v169
	v_exp_f32_e32 v170, v170
	v_exp_f32_e32 v171, v171
	v_fma_f32 v148, -v76, v76, 1.0
	v_fma_f32 v149, -v77, v77, 1.0
	v_fma_f32 v150, -v78, v78, 1.0
	v_fma_f32 v151, -v79, v79, 1.0
	v_add_f32_e32 v168, 1.0, v168
	v_add_f32_e32 v169, 1.0, v169
	v_add_f32_e32 v170, 1.0, v170
	v_add_f32_e32 v171, 1.0, v171
	v_rcp_f32_e32 v168, v168
	v_rcp_f32_e32 v169, v169
	v_rcp_f32_e32 v170, v170
	v_rcp_f32_e32 v171, v171
	v_max_f32_e32 v148, 0, v148
	v_max_f32_e32 v149, 0, v149
	v_max_f32_e32 v150, 0, v150
	v_max_f32_e32 v151, 0, v151
	v_sqrt_f32_e32 v148, v148
	v_sqrt_f32_e32 v149, v149
	v_sqrt_f32_e32 v150, v150
	v_sqrt_f32_e32 v151, v151
	v_mul_f32_e32 v168, v168, v44
	v_mul_f32_e32 v169, v169, v45
	v_mul_f32_e32 v170, v170, v46
	v_mul_f32_e32 v171, v171, v47
	v_mul_f32_e32 v168, v168, v148
	v_mul_f32_e32 v169, v169, v149
	v_mul_f32_e32 v170, v170, v150
	v_mul_f32_e32 v171, v171, v151
	v_fma_f32 v172, v172, s100, v137
	v_fma_f32 v173, v173, s100, v137
	v_fma_f32 v174, v174, s100, v137
	v_fma_f32 v175, v175, s100, v137
	v_exp_f32_e32 v172, v172
	v_exp_f32_e32 v173, v173
	v_exp_f32_e32 v174, v174
	v_exp_f32_e32 v175, v175
	v_fma_f32 v148, -v80, v80, 1.0
	v_fma_f32 v149, -v81, v81, 1.0
	v_fma_f32 v150, -v82, v82, 1.0
	v_fma_f32 v151, -v83, v83, 1.0
	v_add_f32_e32 v172, 1.0, v172
	v_add_f32_e32 v173, 1.0, v173
	v_add_f32_e32 v174, 1.0, v174
	v_add_f32_e32 v175, 1.0, v175
	v_rcp_f32_e32 v172, v172
	v_rcp_f32_e32 v173, v173
	v_rcp_f32_e32 v174, v174
	v_rcp_f32_e32 v175, v175
	v_max_f32_e32 v148, 0, v148
	v_max_f32_e32 v149, 0, v149
	v_max_f32_e32 v150, 0, v150
	v_max_f32_e32 v151, 0, v151
	v_sqrt_f32_e32 v148, v148
	v_sqrt_f32_e32 v149, v149
	v_sqrt_f32_e32 v150, v150
	v_sqrt_f32_e32 v151, v151
	v_mul_f32_e32 v172, v172, v52
	v_mul_f32_e32 v173, v173, v53
	v_mul_f32_e32 v174, v174, v54
	v_mul_f32_e32 v175, v175, v55
	v_mul_f32_e32 v172, v172, v148
	v_mul_f32_e32 v173, v173, v149
	v_mul_f32_e32 v174, v174, v150
	v_mul_f32_e32 v175, v175, v151
	v_fma_f32 v176, v176, s100, v137
	v_fma_f32 v177, v177, s100, v137
	v_fma_f32 v178, v178, s100, v137
	v_fma_f32 v179, v179, s100, v137
	v_exp_f32_e32 v176, v176
	v_exp_f32_e32 v177, v177
	v_exp_f32_e32 v178, v178
	v_exp_f32_e32 v179, v179
	v_fma_f32 v148, -v84, v84, 1.0
	v_fma_f32 v149, -v85, v85, 1.0
	v_fma_f32 v150, -v86, v86, 1.0
	v_fma_f32 v151, -v87, v87, 1.0
	v_add_f32_e32 v176, 1.0, v176
	v_add_f32_e32 v177, 1.0, v177
	v_add_f32_e32 v178, 1.0, v178
	v_add_f32_e32 v179, 1.0, v179
	v_rcp_f32_e32 v176, v176
	v_rcp_f32_e32 v177, v177
	v_rcp_f32_e32 v178, v178
	v_rcp_f32_e32 v179, v179
	v_max_f32_e32 v148, 0, v148
	v_max_f32_e32 v149, 0, v149
	v_max_f32_e32 v150, 0, v150
	v_max_f32_e32 v151, 0, v151
	v_sqrt_f32_e32 v148, v148
	v_sqrt_f32_e32 v149, v149
	v_sqrt_f32_e32 v150, v150
	v_sqrt_f32_e32 v151, v151
	v_mul_f32_e32 v176, v176, v56
	v_mul_f32_e32 v177, v177, v57
	v_mul_f32_e32 v178, v178, v58
	v_mul_f32_e32 v179, v179, v59
	v_mul_f32_e32 v176, v176, v148
	v_mul_f32_e32 v177, v177, v149
	v_mul_f32_e32 v178, v178, v150
	v_mul_f32_e32 v179, v179, v151
	v_fma_f32 v180, v180, s100, v137
	v_fma_f32 v181, v181, s100, v137
	v_fma_f32 v182, v182, s100, v137
	v_fma_f32 v183, v183, s100, v137
	v_exp_f32_e32 v180, v180
	v_exp_f32_e32 v181, v181
	v_exp_f32_e32 v182, v182
	v_exp_f32_e32 v183, v183
	v_fma_f32 v148, -v88, v88, 1.0
	v_fma_f32 v149, -v89, v89, 1.0
	v_fma_f32 v150, -v90, v90, 1.0
	v_fma_f32 v151, -v91, v91, 1.0
	v_add_f32_e32 v180, 1.0, v180
	v_add_f32_e32 v181, 1.0, v181
	v_add_f32_e32 v182, 1.0, v182
	v_add_f32_e32 v183, 1.0, v183
	v_rcp_f32_e32 v180, v180
	v_rcp_f32_e32 v181, v181
	v_rcp_f32_e32 v182, v182
	v_rcp_f32_e32 v183, v183
	v_max_f32_e32 v148, 0, v148
	v_max_f32_e32 v149, 0, v149
	v_max_f32_e32 v150, 0, v150
	v_max_f32_e32 v151, 0, v151
	v_sqrt_f32_e32 v148, v148
	v_sqrt_f32_e32 v149, v149
	v_sqrt_f32_e32 v150, v150
	v_sqrt_f32_e32 v151, v151
	v_mul_f32_e32 v180, v180, v60
	v_mul_f32_e32 v181, v181, v61
	v_mul_f32_e32 v182, v182, v62
	v_mul_f32_e32 v183, v183, v63
	v_mul_f32_e32 v180, v180, v148
	v_mul_f32_e32 v181, v181, v149
	v_mul_f32_e32 v182, v182, v150
	v_mul_f32_e32 v183, v183, v151
	v_fma_f32 v184, v184, s100, v137
	v_fma_f32 v185, v185, s100, v137
	v_fma_f32 v186, v186, s100, v137
	v_fma_f32 v187, v187, s100, v137
	v_exp_f32_e32 v184, v184
	v_exp_f32_e32 v185, v185
	v_exp_f32_e32 v186, v186
	v_exp_f32_e32 v187, v187
	v_fma_f32 v148, -v92, v92, 1.0
	v_fma_f32 v149, -v93, v93, 1.0
	v_fma_f32 v150, -v94, v94, 1.0
	v_fma_f32 v151, -v95, v95, 1.0
	v_add_f32_e32 v184, 1.0, v184
	v_add_f32_e32 v185, 1.0, v185
	v_add_f32_e32 v186, 1.0, v186
	v_add_f32_e32 v187, 1.0, v187
	v_rcp_f32_e32 v184, v184
	v_rcp_f32_e32 v185, v185
	v_rcp_f32_e32 v186, v186
	v_rcp_f32_e32 v187, v187
	v_max_f32_e32 v148, 0, v148
	v_max_f32_e32 v149, 0, v149
	v_max_f32_e32 v150, 0, v150
	v_max_f32_e32 v151, 0, v151
	v_sqrt_f32_e32 v148, v148
	v_sqrt_f32_e32 v149, v149
	v_sqrt_f32_e32 v150, v150
	v_sqrt_f32_e32 v151, v151
	v_mul_f32_e32 v184, v184, v252
	v_mul_f32_e32 v185, v185, v253
	v_mul_f32_e32 v186, v186, v254
	v_mul_f32_e32 v187, v187, v255
	v_mul_f32_e32 v184, v184, v148
	v_mul_f32_e32 v185, v185, v149
	v_mul_f32_e32 v186, v186, v150
	v_mul_f32_e32 v187, v187, v151
	v_fma_f32 v188, v188, s100, v138
	v_fma_f32 v189, v189, s100, v138
	v_fma_f32 v190, v190, s100, v138
	v_fma_f32 v191, v191, s100, v138
	v_exp_f32_e32 v188, v188
	v_exp_f32_e32 v189, v189
	v_exp_f32_e32 v190, v190
	v_exp_f32_e32 v191, v191
	v_fma_f32 v148, -v96, v96, 1.0
	v_fma_f32 v149, -v97, v97, 1.0
	v_fma_f32 v150, -v98, v98, 1.0
	v_fma_f32 v151, -v99, v99, 1.0
	v_add_f32_e32 v188, 1.0, v188
	v_add_f32_e32 v189, 1.0, v189
	v_add_f32_e32 v190, 1.0, v190
	v_add_f32_e32 v191, 1.0, v191
	v_rcp_f32_e32 v188, v188
	v_rcp_f32_e32 v189, v189
	v_rcp_f32_e32 v190, v190
	v_rcp_f32_e32 v191, v191
	v_max_f32_e32 v148, 0, v148
	v_max_f32_e32 v149, 0, v149
	v_max_f32_e32 v150, 0, v150
	v_max_f32_e32 v151, 0, v151
	v_sqrt_f32_e32 v148, v148
	v_sqrt_f32_e32 v149, v149
	v_sqrt_f32_e32 v150, v150
	v_sqrt_f32_e32 v151, v151
	v_mul_f32_e32 v188, v188, v0
	v_mul_f32_e32 v189, v189, v1
	v_mul_f32_e32 v190, v190, v2
	v_mul_f32_e32 v191, v191, v3
	v_mul_f32_e32 v188, v188, v148
	v_mul_f32_e32 v189, v189, v149
	v_mul_f32_e32 v190, v190, v150
	v_mul_f32_e32 v191, v191, v151
	v_fma_f32 v192, v192, s100, v138
	v_fma_f32 v193, v193, s100, v138
	v_fma_f32 v194, v194, s100, v138
	v_fma_f32 v195, v195, s100, v138
	v_exp_f32_e32 v192, v192
	v_exp_f32_e32 v193, v193
	v_exp_f32_e32 v194, v194
	v_exp_f32_e32 v195, v195
	v_fma_f32 v148, -v100, v100, 1.0
	v_fma_f32 v149, -v101, v101, 1.0
	v_fma_f32 v150, -v102, v102, 1.0
	v_fma_f32 v151, -v103, v103, 1.0
	v_add_f32_e32 v192, 1.0, v192
	v_add_f32_e32 v193, 1.0, v193
	v_add_f32_e32 v194, 1.0, v194
	v_add_f32_e32 v195, 1.0, v195
	v_rcp_f32_e32 v192, v192
	v_rcp_f32_e32 v193, v193
	v_rcp_f32_e32 v194, v194
	v_rcp_f32_e32 v195, v195
	v_max_f32_e32 v148, 0, v148
	v_max_f32_e32 v149, 0, v149
	v_max_f32_e32 v150, 0, v150
	v_max_f32_e32 v151, 0, v151
	v_sqrt_f32_e32 v148, v148
	v_sqrt_f32_e32 v149, v149
	v_sqrt_f32_e32 v150, v150
	v_sqrt_f32_e32 v151, v151
	v_mul_f32_e32 v192, v192, v4
	v_mul_f32_e32 v193, v193, v5
	v_mul_f32_e32 v194, v194, v6
	v_mul_f32_e32 v195, v195, v7
	v_mul_f32_e32 v192, v192, v148
	v_mul_f32_e32 v193, v193, v149
	v_mul_f32_e32 v194, v194, v150
	v_mul_f32_e32 v195, v195, v151
	v_fma_f32 v196, v196, s100, v138
	v_fma_f32 v197, v197, s100, v138
	v_fma_f32 v198, v198, s100, v138
	v_fma_f32 v199, v199, s100, v138
	v_exp_f32_e32 v196, v196
	v_exp_f32_e32 v197, v197
	v_exp_f32_e32 v198, v198
	v_exp_f32_e32 v199, v199
	v_fma_f32 v148, -v104, v104, 1.0
	v_fma_f32 v149, -v105, v105, 1.0
	v_fma_f32 v150, -v106, v106, 1.0
	v_fma_f32 v151, -v107, v107, 1.0
	v_add_f32_e32 v196, 1.0, v196
	v_add_f32_e32 v197, 1.0, v197
	v_add_f32_e32 v198, 1.0, v198
	v_add_f32_e32 v199, 1.0, v199
	v_rcp_f32_e32 v196, v196
	v_rcp_f32_e32 v197, v197
	v_rcp_f32_e32 v198, v198
	v_rcp_f32_e32 v199, v199
	v_max_f32_e32 v148, 0, v148
	v_max_f32_e32 v149, 0, v149
	v_max_f32_e32 v150, 0, v150
	v_max_f32_e32 v151, 0, v151
	v_sqrt_f32_e32 v148, v148
	v_sqrt_f32_e32 v149, v149
	v_sqrt_f32_e32 v150, v150
	v_sqrt_f32_e32 v151, v151
	v_mul_f32_e32 v196, v196, v8
	v_mul_f32_e32 v197, v197, v9
	v_mul_f32_e32 v198, v198, v10
	v_mul_f32_e32 v199, v199, v11
	v_mul_f32_e32 v196, v196, v148
	v_mul_f32_e32 v197, v197, v149
	v_mul_f32_e32 v198, v198, v150
	v_mul_f32_e32 v199, v199, v151
	v_fma_f32 v200, v200, s100, v138
	v_fma_f32 v201, v201, s100, v138
	v_fma_f32 v202, v202, s100, v138
	v_fma_f32 v203, v203, s100, v138
	v_exp_f32_e32 v200, v200
	v_exp_f32_e32 v201, v201
	v_exp_f32_e32 v202, v202
	v_exp_f32_e32 v203, v203
	v_fma_f32 v148, -v108, v108, 1.0
	v_fma_f32 v149, -v109, v109, 1.0
	v_fma_f32 v150, -v110, v110, 1.0
	v_fma_f32 v151, -v111, v111, 1.0
	v_add_f32_e32 v200, 1.0, v200
	v_add_f32_e32 v201, 1.0, v201
	v_add_f32_e32 v202, 1.0, v202
	v_add_f32_e32 v203, 1.0, v203
	v_rcp_f32_e32 v200, v200
	v_rcp_f32_e32 v201, v201
	v_rcp_f32_e32 v202, v202
	v_rcp_f32_e32 v203, v203
	v_max_f32_e32 v148, 0, v148
	v_max_f32_e32 v149, 0, v149
	v_max_f32_e32 v150, 0, v150
	v_max_f32_e32 v151, 0, v151
	v_sqrt_f32_e32 v148, v148
	v_sqrt_f32_e32 v149, v149
	v_sqrt_f32_e32 v150, v150
	v_sqrt_f32_e32 v151, v151
	v_mul_f32_e32 v200, v200, v12
	v_mul_f32_e32 v201, v201, v13
	v_mul_f32_e32 v202, v202, v14
	v_mul_f32_e32 v203, v203, v15
	v_mul_f32_e32 v200, v200, v148
	v_mul_f32_e32 v201, v201, v149
	v_mul_f32_e32 v202, v202, v150
	v_mul_f32_e32 v203, v203, v151
	v_fma_f32 v204, v204, s100, v139
	v_fma_f32 v205, v205, s100, v139
	v_fma_f32 v206, v206, s100, v139
	v_fma_f32 v207, v207, s100, v139
	v_exp_f32_e32 v204, v204
	v_exp_f32_e32 v205, v205
	v_exp_f32_e32 v206, v206
	v_exp_f32_e32 v207, v207
	v_fma_f32 v148, -v112, v112, 1.0
	v_fma_f32 v149, -v113, v113, 1.0
	v_fma_f32 v150, -v114, v114, 1.0
	v_fma_f32 v151, -v115, v115, 1.0
	v_add_f32_e32 v204, 1.0, v204
	v_add_f32_e32 v205, 1.0, v205
	v_add_f32_e32 v206, 1.0, v206
	v_add_f32_e32 v207, 1.0, v207
	v_rcp_f32_e32 v204, v204
	v_rcp_f32_e32 v205, v205
	v_rcp_f32_e32 v206, v206
	v_rcp_f32_e32 v207, v207
	v_max_f32_e32 v148, 0, v148
	v_max_f32_e32 v149, 0, v149
	v_max_f32_e32 v150, 0, v150
	v_max_f32_e32 v151, 0, v151
	v_sqrt_f32_e32 v148, v148
	v_sqrt_f32_e32 v149, v149
	v_sqrt_f32_e32 v150, v150
	v_sqrt_f32_e32 v151, v151
	v_mul_f32_e32 v204, v204, v16
	v_mul_f32_e32 v205, v205, v17
	v_mul_f32_e32 v206, v206, v18
	v_mul_f32_e32 v207, v207, v19
	v_mul_f32_e32 v204, v204, v148
	v_mul_f32_e32 v205, v205, v149
	v_mul_f32_e32 v206, v206, v150
	v_mul_f32_e32 v207, v207, v151
	v_fma_f32 v208, v208, s100, v139
	v_fma_f32 v209, v209, s100, v139
	v_fma_f32 v210, v210, s100, v139
	v_fma_f32 v211, v211, s100, v139
	v_exp_f32_e32 v208, v208
	v_exp_f32_e32 v209, v209
	v_exp_f32_e32 v210, v210
	v_exp_f32_e32 v211, v211
	v_fma_f32 v148, -v116, v116, 1.0
	v_fma_f32 v149, -v117, v117, 1.0
	v_fma_f32 v150, -v118, v118, 1.0
	v_fma_f32 v151, -v119, v119, 1.0
	v_add_f32_e32 v208, 1.0, v208
	v_add_f32_e32 v209, 1.0, v209
	v_add_f32_e32 v210, 1.0, v210
	v_add_f32_e32 v211, 1.0, v211
	v_rcp_f32_e32 v208, v208
	v_rcp_f32_e32 v209, v209
	v_rcp_f32_e32 v210, v210
	v_rcp_f32_e32 v211, v211
	v_max_f32_e32 v148, 0, v148
	v_max_f32_e32 v149, 0, v149
	v_max_f32_e32 v150, 0, v150
	v_max_f32_e32 v151, 0, v151
	v_sqrt_f32_e32 v148, v148
	v_sqrt_f32_e32 v149, v149
	v_sqrt_f32_e32 v150, v150
	v_sqrt_f32_e32 v151, v151
	v_mul_f32_e32 v208, v208, v20
	v_mul_f32_e32 v209, v209, v21
	v_mul_f32_e32 v210, v210, v22
	v_mul_f32_e32 v211, v211, v23
	v_mul_f32_e32 v208, v208, v148
	v_mul_f32_e32 v209, v209, v149
	v_mul_f32_e32 v210, v210, v150
	v_mul_f32_e32 v211, v211, v151
	v_fma_f32 v212, v212, s100, v139
	v_fma_f32 v213, v213, s100, v139
	v_fma_f32 v214, v214, s100, v139
	v_fma_f32 v215, v215, s100, v139
	v_exp_f32_e32 v212, v212
	v_exp_f32_e32 v213, v213
	v_exp_f32_e32 v214, v214
	v_exp_f32_e32 v215, v215
	v_fma_f32 v148, -v120, v120, 1.0
	v_fma_f32 v149, -v121, v121, 1.0
	v_fma_f32 v150, -v122, v122, 1.0
	v_fma_f32 v151, -v123, v123, 1.0
	v_add_f32_e32 v212, 1.0, v212
	v_add_f32_e32 v213, 1.0, v213
	v_add_f32_e32 v214, 1.0, v214
	v_add_f32_e32 v215, 1.0, v215
	v_rcp_f32_e32 v212, v212
	v_rcp_f32_e32 v213, v213
	v_rcp_f32_e32 v214, v214
	v_rcp_f32_e32 v215, v215
	v_max_f32_e32 v148, 0, v148
	v_max_f32_e32 v149, 0, v149
	v_max_f32_e32 v150, 0, v150
	v_max_f32_e32 v151, 0, v151
	v_sqrt_f32_e32 v148, v148
	v_sqrt_f32_e32 v149, v149
	v_sqrt_f32_e32 v150, v150
	v_sqrt_f32_e32 v151, v151
	v_mul_f32_e32 v212, v212, v24
	v_mul_f32_e32 v213, v213, v25
	v_mul_f32_e32 v214, v214, v26
	v_mul_f32_e32 v215, v215, v27
	v_mul_f32_e32 v212, v212, v148
	v_mul_f32_e32 v213, v213, v149
	v_mul_f32_e32 v214, v214, v150
	v_mul_f32_e32 v215, v215, v151
	v_fma_f32 v216, v216, s100, v139
	v_fma_f32 v217, v217, s100, v139
	v_fma_f32 v218, v218, s100, v139
	v_fma_f32 v219, v219, s100, v139
	v_exp_f32_e32 v216, v216
	v_exp_f32_e32 v217, v217
	v_exp_f32_e32 v218, v218
	v_exp_f32_e32 v219, v219
	v_fma_f32 v148, -v124, v124, 1.0
	v_fma_f32 v149, -v125, v125, 1.0
	v_fma_f32 v150, -v126, v126, 1.0
	v_fma_f32 v151, -v127, v127, 1.0
	v_add_f32_e32 v216, 1.0, v216
	v_add_f32_e32 v217, 1.0, v217
	v_add_f32_e32 v218, 1.0, v218
	v_add_f32_e32 v219, 1.0, v219
	v_rcp_f32_e32 v216, v216
	v_rcp_f32_e32 v217, v217
	v_rcp_f32_e32 v218, v218
	v_rcp_f32_e32 v219, v219
	v_max_f32_e32 v148, 0, v148
	v_max_f32_e32 v149, 0, v149
	v_max_f32_e32 v150, 0, v150
	v_max_f32_e32 v151, 0, v151
	v_sqrt_f32_e32 v148, v148
	v_sqrt_f32_e32 v149, v149
	v_sqrt_f32_e32 v150, v150
	v_sqrt_f32_e32 v151, v151
	v_mul_f32_e32 v216, v216, v28
	v_mul_f32_e32 v217, v217, v29
	v_mul_f32_e32 v218, v218, v30
	v_mul_f32_e32 v219, v219, v31
	v_mul_f32_e32 v216, v216, v148
	v_mul_f32_e32 v217, v217, v149
	v_mul_f32_e32 v218, v218, v150
	v_mul_f32_e32 v219, v219, v151
	v_fmac_f32_e32 v157, v65, v156
	v_fmac_f32_e32 v173, v81, v172
	v_fmac_f32_e32 v189, v97, v188
	v_fmac_f32_e32 v205, v113, v204
	v_mul_f32_e32 v65, v64, v65
	v_mul_f32_e32 v81, v80, v81
	v_mul_f32_e32 v97, v96, v97
	v_mul_f32_e32 v113, v112, v113
	v_fmac_f32_e32 v158, v66, v157
	v_fmac_f32_e32 v174, v82, v173
	v_fmac_f32_e32 v190, v98, v189
	v_fmac_f32_e32 v206, v114, v205
	v_mul_f32_e32 v66, v65, v66
	v_mul_f32_e32 v82, v81, v82
	v_mul_f32_e32 v98, v97, v98
	v_mul_f32_e32 v114, v113, v114
	v_fmac_f32_e32 v159, v67, v158
	v_fmac_f32_e32 v175, v83, v174
	v_fmac_f32_e32 v191, v99, v190
	v_fmac_f32_e32 v207, v115, v206
	v_mul_f32_e32 v67, v66, v67
	v_mul_f32_e32 v83, v82, v83
	v_mul_f32_e32 v99, v98, v99
	v_mul_f32_e32 v115, v114, v115
	v_fmac_f32_e32 v160, v68, v159
	v_fmac_f32_e32 v176, v84, v175
	v_fmac_f32_e32 v192, v100, v191
	v_fmac_f32_e32 v208, v116, v207
	v_mul_f32_e32 v68, v67, v68
	v_mul_f32_e32 v84, v83, v84
	v_mul_f32_e32 v100, v99, v100
	v_mul_f32_e32 v116, v115, v116
	v_fmac_f32_e32 v161, v69, v160
	v_fmac_f32_e32 v177, v85, v176
	v_fmac_f32_e32 v193, v101, v192
	v_fmac_f32_e32 v209, v117, v208
	v_mul_f32_e32 v69, v68, v69
	v_mul_f32_e32 v85, v84, v85
	v_mul_f32_e32 v101, v100, v101
	v_mul_f32_e32 v117, v116, v117
	v_fmac_f32_e32 v162, v70, v161
	v_fmac_f32_e32 v178, v86, v177
	v_fmac_f32_e32 v194, v102, v193
	v_fmac_f32_e32 v210, v118, v209
	v_mul_f32_e32 v70, v69, v70
	v_mul_f32_e32 v86, v85, v86
	v_mul_f32_e32 v102, v101, v102
	v_mul_f32_e32 v118, v117, v118
	v_fmac_f32_e32 v163, v71, v162
	v_fmac_f32_e32 v179, v87, v178
	v_fmac_f32_e32 v195, v103, v194
	v_fmac_f32_e32 v211, v119, v210
	v_mul_f32_e32 v71, v70, v71
	v_mul_f32_e32 v87, v86, v87
	v_mul_f32_e32 v103, v102, v103
	v_mul_f32_e32 v119, v118, v119
	v_fmac_f32_e32 v164, v72, v163
	v_fmac_f32_e32 v180, v88, v179
	v_fmac_f32_e32 v196, v104, v195
	v_fmac_f32_e32 v212, v120, v211
	v_mul_f32_e32 v72, v71, v72
	v_mul_f32_e32 v88, v87, v88
	v_mul_f32_e32 v104, v103, v104
	v_mul_f32_e32 v120, v119, v120
	v_fmac_f32_e32 v165, v73, v164
	v_fmac_f32_e32 v181, v89, v180
	v_fmac_f32_e32 v197, v105, v196
	v_fmac_f32_e32 v213, v121, v212
	v_mul_f32_e32 v73, v72, v73
	v_mul_f32_e32 v89, v88, v89
	v_mul_f32_e32 v105, v104, v105
	v_mul_f32_e32 v121, v120, v121
	v_fmac_f32_e32 v166, v74, v165
	v_fmac_f32_e32 v182, v90, v181
	v_fmac_f32_e32 v198, v106, v197
	v_fmac_f32_e32 v214, v122, v213
	v_mul_f32_e32 v74, v73, v74
	v_mul_f32_e32 v90, v89, v90
	v_mul_f32_e32 v106, v105, v106
	v_mul_f32_e32 v122, v121, v122
	v_fmac_f32_e32 v167, v75, v166
	v_fmac_f32_e32 v183, v91, v182
	v_fmac_f32_e32 v199, v107, v198
	v_fmac_f32_e32 v215, v123, v214
	v_mul_f32_e32 v75, v74, v75
	v_mul_f32_e32 v91, v90, v91
	v_mul_f32_e32 v107, v106, v107
	v_mul_f32_e32 v123, v122, v123
	v_fmac_f32_e32 v168, v76, v167
	v_fmac_f32_e32 v184, v92, v183
	v_fmac_f32_e32 v200, v108, v199
	v_fmac_f32_e32 v216, v124, v215
	v_mul_f32_e32 v76, v75, v76
	v_mul_f32_e32 v92, v91, v92
	v_mul_f32_e32 v108, v107, v108
	v_mul_f32_e32 v124, v123, v124
	v_fmac_f32_e32 v169, v77, v168
	v_fmac_f32_e32 v185, v93, v184
	v_fmac_f32_e32 v201, v109, v200
	v_fmac_f32_e32 v217, v125, v216
	v_mul_f32_e32 v77, v76, v77
	v_mul_f32_e32 v93, v92, v93
	v_mul_f32_e32 v109, v108, v109
	v_mul_f32_e32 v125, v124, v125
	v_fmac_f32_e32 v170, v78, v169
	v_fmac_f32_e32 v186, v94, v185
	v_fmac_f32_e32 v202, v110, v201
	v_fmac_f32_e32 v218, v126, v217
	v_mul_f32_e32 v78, v77, v78
	v_mul_f32_e32 v94, v93, v94
	v_mul_f32_e32 v110, v109, v110
	v_mul_f32_e32 v126, v125, v126
	v_fmac_f32_e32 v171, v79, v170
	v_fmac_f32_e32 v187, v95, v186
	v_fmac_f32_e32 v203, v111, v202
	v_fmac_f32_e32 v219, v127, v218
	v_mul_f32_e32 v79, v78, v79
	v_mul_f32_e32 v95, v94, v95
	v_mul_f32_e32 v111, v110, v111
	v_mul_f32_e32 v127, v126, v127
	s_nop 1
	ds_bpermute_b32 v0, v225, v171
	ds_bpermute_b32 v1, v225, v79
	ds_bpermute_b32 v2, v226, v171
	ds_bpermute_b32 v3, v226, v79
	ds_bpermute_b32 v4, v227, v171
	ds_bpermute_b32 v5, v227, v79
	ds_bpermute_b32 v6, v225, v187
	ds_bpermute_b32 v7, v225, v95
	ds_bpermute_b32 v8, v226, v187
	ds_bpermute_b32 v9, v226, v95
	ds_bpermute_b32 v10, v227, v187
	ds_bpermute_b32 v11, v227, v95
	ds_bpermute_b32 v12, v225, v203
	ds_bpermute_b32 v13, v225, v111
	ds_bpermute_b32 v14, v226, v203
	ds_bpermute_b32 v15, v226, v111
	ds_bpermute_b32 v16, v227, v203
	ds_bpermute_b32 v17, v227, v111
	ds_bpermute_b32 v18, v225, v219
	ds_bpermute_b32 v19, v225, v127
	ds_bpermute_b32 v20, v226, v219
	ds_bpermute_b32 v21, v226, v127
	ds_bpermute_b32 v22, v227, v219
	ds_bpermute_b32 v23, v227, v127
	s_waitcnt lgkmcnt(0)
	v_cndmask_b32_e64 v4, 0, v4, s[98:99]
	v_cndmask_b32_e64 v5, 1.0, v5, s[98:99]
	v_cndmask_b32_e64 v2, 0, v2, s[96:97]
	v_cndmask_b32_e64 v3, 1.0, v3, s[96:97]
	v_cndmask_b32_e64 v0, 0, v0, s[94:95]
	v_cndmask_b32_e64 v1, 1.0, v1, s[94:95]
	v_cndmask_b32_e64 v10, 0, v10, s[98:99]
	v_cndmask_b32_e64 v11, 1.0, v11, s[98:99]
	v_cndmask_b32_e64 v8, 0, v8, s[96:97]
	v_cndmask_b32_e64 v9, 1.0, v9, s[96:97]
	v_cndmask_b32_e64 v6, 0, v6, s[94:95]
	v_cndmask_b32_e64 v7, 1.0, v7, s[94:95]
	v_cndmask_b32_e64 v16, 0, v16, s[98:99]
	v_cndmask_b32_e64 v17, 1.0, v17, s[98:99]
	v_cndmask_b32_e64 v14, 0, v14, s[96:97]
	v_cndmask_b32_e64 v15, 1.0, v15, s[96:97]
	v_cndmask_b32_e64 v12, 0, v12, s[94:95]
	v_cndmask_b32_e64 v13, 1.0, v13, s[94:95]
	v_cndmask_b32_e64 v22, 0, v22, s[98:99]
	v_cndmask_b32_e64 v23, 1.0, v23, s[98:99]
	v_cndmask_b32_e64 v20, 0, v20, s[96:97]
	v_cndmask_b32_e64 v21, 1.0, v21, s[96:97]
	v_cndmask_b32_e64 v18, 0, v18, s[94:95]
	v_cndmask_b32_e64 v19, 1.0, v19, s[94:95]
	v_fma_f32 v24, v3, v4, v2
	v_mul_f32_e32 v25, v5, v3
	v_fma_f32 v26, v9, v10, v8
	v_mul_f32_e32 v27, v11, v9
	v_fma_f32 v28, v15, v16, v14
	v_mul_f32_e32 v29, v17, v15
	v_fma_f32 v30, v21, v22, v20
	v_mul_f32_e32 v31, v23, v21
	v_fma_f32 v24, v1, v24, v0
	v_mul_f32_e32 v25, v25, v1
	v_fma_f32 v26, v7, v26, v6
	v_mul_f32_e32 v27, v27, v7
	v_fma_f32 v28, v13, v28, v12
	v_mul_f32_e32 v29, v29, v13
	v_fma_f32 v30, v19, v30, v18
	v_mul_f32_e32 v31, v31, v19
	v_fmac_f32_e32 v156, v64, v24
	v_fmac_f32_e32 v172, v80, v26
	v_fmac_f32_e32 v188, v96, v28
	v_fmac_f32_e32 v204, v112, v30
	v_mul_f32_e32 v64, v64, v25
	v_mul_f32_e32 v80, v80, v27
	v_mul_f32_e32 v96, v96, v29
	v_mul_f32_e32 v112, v112, v31
	v_fmac_f32_e32 v157, v65, v24
	v_fmac_f32_e32 v173, v81, v26
	v_fmac_f32_e32 v189, v97, v28
	v_fmac_f32_e32 v205, v113, v30
	v_mul_f32_e32 v65, v65, v25
	v_mul_f32_e32 v81, v81, v27
	v_mul_f32_e32 v97, v97, v29
	v_mul_f32_e32 v113, v113, v31
	v_fmac_f32_e32 v158, v66, v24
	v_fmac_f32_e32 v174, v82, v26
	v_fmac_f32_e32 v190, v98, v28
	v_fmac_f32_e32 v206, v114, v30
	v_mul_f32_e32 v66, v66, v25
	v_mul_f32_e32 v82, v82, v27
	v_mul_f32_e32 v98, v98, v29
	v_mul_f32_e32 v114, v114, v31
	v_fmac_f32_e32 v159, v67, v24
	v_fmac_f32_e32 v175, v83, v26
	v_fmac_f32_e32 v191, v99, v28
	v_fmac_f32_e32 v207, v115, v30
	v_mul_f32_e32 v67, v67, v25
	v_mul_f32_e32 v83, v83, v27
	v_mul_f32_e32 v99, v99, v29
	v_mul_f32_e32 v115, v115, v31
	v_fmac_f32_e32 v160, v68, v24
	v_fmac_f32_e32 v176, v84, v26
	v_fmac_f32_e32 v192, v100, v28
	v_fmac_f32_e32 v208, v116, v30
	v_mul_f32_e32 v68, v68, v25
	v_mul_f32_e32 v84, v84, v27
	v_mul_f32_e32 v100, v100, v29
	v_mul_f32_e32 v116, v116, v31
	v_fmac_f32_e32 v161, v69, v24
	v_fmac_f32_e32 v177, v85, v26
	v_fmac_f32_e32 v193, v101, v28
	v_fmac_f32_e32 v209, v117, v30
	v_mul_f32_e32 v69, v69, v25
	v_mul_f32_e32 v85, v85, v27
	v_mul_f32_e32 v101, v101, v29
	v_mul_f32_e32 v117, v117, v31
	v_fmac_f32_e32 v162, v70, v24
	v_fmac_f32_e32 v178, v86, v26
	v_fmac_f32_e32 v194, v102, v28
	v_fmac_f32_e32 v210, v118, v30
	v_mul_f32_e32 v70, v70, v25
	v_mul_f32_e32 v86, v86, v27
	v_mul_f32_e32 v102, v102, v29
	v_mul_f32_e32 v118, v118, v31
	v_fmac_f32_e32 v163, v71, v24
	v_fmac_f32_e32 v179, v87, v26
	v_fmac_f32_e32 v195, v103, v28
	v_fmac_f32_e32 v211, v119, v30
	v_mul_f32_e32 v71, v71, v25
	v_mul_f32_e32 v87, v87, v27
	v_mul_f32_e32 v103, v103, v29
	v_mul_f32_e32 v119, v119, v31
	v_fmac_f32_e32 v164, v72, v24
	v_fmac_f32_e32 v180, v88, v26
	v_fmac_f32_e32 v196, v104, v28
	v_fmac_f32_e32 v212, v120, v30
	v_mul_f32_e32 v72, v72, v25
	v_mul_f32_e32 v88, v88, v27
	v_mul_f32_e32 v104, v104, v29
	v_mul_f32_e32 v120, v120, v31
	v_fmac_f32_e32 v165, v73, v24
	v_fmac_f32_e32 v181, v89, v26
	v_fmac_f32_e32 v197, v105, v28
	v_fmac_f32_e32 v213, v121, v30
	v_mul_f32_e32 v73, v73, v25
	v_mul_f32_e32 v89, v89, v27
	v_mul_f32_e32 v105, v105, v29
	v_mul_f32_e32 v121, v121, v31
	v_fmac_f32_e32 v166, v74, v24
	v_fmac_f32_e32 v182, v90, v26
	v_fmac_f32_e32 v198, v106, v28
	v_fmac_f32_e32 v214, v122, v30
	v_mul_f32_e32 v74, v74, v25
	v_mul_f32_e32 v90, v90, v27
	v_mul_f32_e32 v106, v106, v29
	v_mul_f32_e32 v122, v122, v31
	v_fmac_f32_e32 v167, v75, v24
	v_fmac_f32_e32 v183, v91, v26
	v_fmac_f32_e32 v199, v107, v28
	v_fmac_f32_e32 v215, v123, v30
	v_mul_f32_e32 v75, v75, v25
	v_mul_f32_e32 v91, v91, v27
	v_mul_f32_e32 v107, v107, v29
	v_mul_f32_e32 v123, v123, v31
	v_fmac_f32_e32 v168, v76, v24
	v_fmac_f32_e32 v184, v92, v26
	v_fmac_f32_e32 v200, v108, v28
	v_fmac_f32_e32 v216, v124, v30
	v_mul_f32_e32 v76, v76, v25
	v_mul_f32_e32 v92, v92, v27
	v_mul_f32_e32 v108, v108, v29
	v_mul_f32_e32 v124, v124, v31
	v_fmac_f32_e32 v169, v77, v24
	v_fmac_f32_e32 v185, v93, v26
	v_fmac_f32_e32 v201, v109, v28
	v_fmac_f32_e32 v217, v125, v30
	v_mul_f32_e32 v77, v77, v25
	v_mul_f32_e32 v93, v93, v27
	v_mul_f32_e32 v109, v109, v29
	v_mul_f32_e32 v125, v125, v31
	v_fmac_f32_e32 v170, v78, v24
	v_fmac_f32_e32 v186, v94, v26
	v_fmac_f32_e32 v202, v110, v28
	v_fmac_f32_e32 v218, v126, v30
	v_mul_f32_e32 v78, v78, v25
	v_mul_f32_e32 v94, v94, v27
	v_mul_f32_e32 v110, v110, v29
	v_mul_f32_e32 v126, v126, v31
	v_fmac_f32_e32 v171, v79, v24
	v_fmac_f32_e32 v187, v95, v26
	v_fmac_f32_e32 v203, v111, v28
	v_fmac_f32_e32 v219, v127, v30
	v_mul_f32_e32 v79, v79, v25
	v_mul_f32_e32 v95, v95, v27
	v_mul_f32_e32 v111, v111, v29
	v_mul_f32_e32 v127, v127, v31
	s_mov_b64 exec, s[98:99]
	global_store_dword v224, v79, s[14:15]
	global_store_dword v224, v171, s[16:17]
	global_store_dword v224, v95, s[14:15] offset:64
	global_store_dword v224, v187, s[16:17] offset:64
	global_store_dword v224, v111, s[14:15] offset:128
	global_store_dword v224, v203, s[16:17] offset:128
	global_store_dword v224, v127, s[14:15] offset:192
	global_store_dword v224, v219, s[16:17] offset:192
	s_mov_b64 exec, -1
	v_cvt_pk_bf16_f32 v0, v156, v157
	v_cvt_pk_bf16_f32 v1, v64, v65
	ds_write_b16 v147, v0 offset:0
	ds_write_b16_d16_hi v147, v0 offset:1040
	ds_write_b16 v220, v1 offset:0
	ds_write_b16_d16_hi v220, v1 offset:128
	v_cvt_pk_bf16_f32 v2, v158, v159
	v_cvt_pk_bf16_f32 v3, v66, v67
	ds_write_b16 v147, v2 offset:2080
	ds_write_b16_d16_hi v147, v2 offset:3120
	ds_write_b16 v220, v3 offset:256
	ds_write_b16_d16_hi v220, v3 offset:384
	v_cvt_pk_bf16_f32 v4, v160, v161
	v_cvt_pk_bf16_f32 v5, v68, v69
	ds_write_b16 v147, v4 offset:4160
	ds_write_b16_d16_hi v147, v4 offset:5200
	ds_write_b16 v220, v5 offset:512
	ds_write_b16_d16_hi v220, v5 offset:640
	v_cvt_pk_bf16_f32 v6, v162, v163
	v_cvt_pk_bf16_f32 v7, v70, v71
	ds_write_b16 v147, v6 offset:6240
	ds_write_b16_d16_hi v147, v6 offset:7280
	ds_write_b16 v220, v7 offset:768
	ds_write_b16_d16_hi v220, v7 offset:896
	v_cvt_pk_bf16_f32 v8, v164, v165
	v_cvt_pk_bf16_f32 v9, v72, v73
	ds_write_b16 v147, v8 offset:8320
	ds_write_b16_d16_hi v147, v8 offset:9360
	ds_write_b16 v220, v9 offset:1024
	ds_write_b16_d16_hi v220, v9 offset:1152
	v_cvt_pk_bf16_f32 v10, v166, v167
	v_cvt_pk_bf16_f32 v11, v74, v75
	ds_write_b16 v147, v10 offset:10400
	ds_write_b16_d16_hi v147, v10 offset:11440
	ds_write_b16 v220, v11 offset:1280
	ds_write_b16_d16_hi v220, v11 offset:1408
	v_cvt_pk_bf16_f32 v12, v168, v169
	v_cvt_pk_bf16_f32 v13, v76, v77
	ds_write_b16 v147, v12 offset:12480
	ds_write_b16_d16_hi v147, v12 offset:13520
	ds_write_b16 v220, v13 offset:1536
	ds_write_b16_d16_hi v220, v13 offset:1664
	v_cvt_pk_bf16_f32 v14, v170, v171
	v_cvt_pk_bf16_f32 v15, v78, v79
	ds_write_b16 v147, v14 offset:14560
	ds_write_b16_d16_hi v147, v14 offset:15600
	ds_write_b16 v220, v15 offset:1792
	ds_write_b16_d16_hi v220, v15 offset:1920
	v_cvt_pk_bf16_f32 v16, v172, v173
	v_cvt_pk_bf16_f32 v17, v80, v81
	ds_write_b16 v147, v16 offset:32
	ds_write_b16_d16_hi v147, v16 offset:1072
	ds_write_b16 v220, v17 offset:32
	ds_write_b16_d16_hi v220, v17 offset:160
	v_cvt_pk_bf16_f32 v18, v174, v175
	v_cvt_pk_bf16_f32 v19, v82, v83
	ds_write_b16 v147, v18 offset:2112
	ds_write_b16_d16_hi v147, v18 offset:3152
	ds_write_b16 v220, v19 offset:288
	ds_write_b16_d16_hi v220, v19 offset:416
	v_cvt_pk_bf16_f32 v20, v176, v177
	v_cvt_pk_bf16_f32 v21, v84, v85
	ds_write_b16 v147, v20 offset:4192
	ds_write_b16_d16_hi v147, v20 offset:5232
	ds_write_b16 v220, v21 offset:544
	ds_write_b16_d16_hi v220, v21 offset:672
	v_cvt_pk_bf16_f32 v22, v178, v179
	v_cvt_pk_bf16_f32 v23, v86, v87
	ds_write_b16 v147, v22 offset:6272
	ds_write_b16_d16_hi v147, v22 offset:7312
	ds_write_b16 v220, v23 offset:800
	ds_write_b16_d16_hi v220, v23 offset:928
	v_cvt_pk_bf16_f32 v0, v180, v181
	v_cvt_pk_bf16_f32 v1, v88, v89
	ds_write_b16 v147, v0 offset:8352
	ds_write_b16_d16_hi v147, v0 offset:9392
	ds_write_b16 v220, v1 offset:1056
	ds_write_b16_d16_hi v220, v1 offset:1184
	v_cvt_pk_bf16_f32 v2, v182, v183
	v_cvt_pk_bf16_f32 v3, v90, v91
	ds_write_b16 v147, v2 offset:10432
	ds_write_b16_d16_hi v147, v2 offset:11472
	ds_write_b16 v220, v3 offset:1312
	ds_write_b16_d16_hi v220, v3 offset:1440
	v_cvt_pk_bf16_f32 v4, v184, v185
	v_cvt_pk_bf16_f32 v5, v92, v93
	ds_write_b16 v147, v4 offset:12512
	ds_write_b16_d16_hi v147, v4 offset:13552
	ds_write_b16 v220, v5 offset:1568
	ds_write_b16_d16_hi v220, v5 offset:1696
	v_cvt_pk_bf16_f32 v6, v186, v187
	v_cvt_pk_bf16_f32 v7, v94, v95
	ds_write_b16 v147, v6 offset:14592
	ds_write_b16_d16_hi v147, v6 offset:15632
	ds_write_b16 v220, v7 offset:1824
	ds_write_b16_d16_hi v220, v7 offset:1952
	v_cvt_pk_bf16_f32 v8, v188, v189
	v_cvt_pk_bf16_f32 v9, v96, v97
	ds_write_b16 v147, v8 offset:64
	ds_write_b16_d16_hi v147, v8 offset:1104
	ds_write_b16 v220, v9 offset:64
	ds_write_b16_d16_hi v220, v9 offset:192
	v_cvt_pk_bf16_f32 v10, v190, v191
	v_cvt_pk_bf16_f32 v11, v98, v99
	ds_write_b16 v147, v10 offset:2144
	ds_write_b16_d16_hi v147, v10 offset:3184
	ds_write_b16 v220, v11 offset:320
	ds_write_b16_d16_hi v220, v11 offset:448
	v_cvt_pk_bf16_f32 v12, v192, v193
	v_cvt_pk_bf16_f32 v13, v100, v101
	ds_write_b16 v147, v12 offset:4224
	ds_write_b16_d16_hi v147, v12 offset:5264
	ds_write_b16 v220, v13 offset:576
	ds_write_b16_d16_hi v220, v13 offset:704
	v_cvt_pk_bf16_f32 v14, v194, v195
	v_cvt_pk_bf16_f32 v15, v102, v103
	ds_write_b16 v147, v14 offset:6304
	ds_write_b16_d16_hi v147, v14 offset:7344
	ds_write_b16 v220, v15 offset:832
	ds_write_b16_d16_hi v220, v15 offset:960
	v_cvt_pk_bf16_f32 v16, v196, v197
	v_cvt_pk_bf16_f32 v17, v104, v105
	ds_write_b16 v147, v16 offset:8384
	ds_write_b16_d16_hi v147, v16 offset:9424
	ds_write_b16 v220, v17 offset:1088
	ds_write_b16_d16_hi v220, v17 offset:1216
	v_cvt_pk_bf16_f32 v18, v198, v199
	v_cvt_pk_bf16_f32 v19, v106, v107
	ds_write_b16 v147, v18 offset:10464
	ds_write_b16_d16_hi v147, v18 offset:11504
	ds_write_b16 v220, v19 offset:1344
	ds_write_b16_d16_hi v220, v19 offset:1472
	v_cvt_pk_bf16_f32 v20, v200, v201
	v_cvt_pk_bf16_f32 v21, v108, v109
	ds_write_b16 v147, v20 offset:12544
	ds_write_b16_d16_hi v147, v20 offset:13584
	ds_write_b16 v220, v21 offset:1600
	ds_write_b16_d16_hi v220, v21 offset:1728
	v_cvt_pk_bf16_f32 v22, v202, v203
	v_cvt_pk_bf16_f32 v23, v110, v111
	ds_write_b16 v147, v22 offset:14624
	ds_write_b16_d16_hi v147, v22 offset:15664
	ds_write_b16 v220, v23 offset:1856
	ds_write_b16_d16_hi v220, v23 offset:1984
	v_cvt_pk_bf16_f32 v0, v204, v205
	v_cvt_pk_bf16_f32 v1, v112, v113
	ds_write_b16 v147, v0 offset:96
	ds_write_b16_d16_hi v147, v0 offset:1136
	ds_write_b16 v220, v1 offset:96
	ds_write_b16_d16_hi v220, v1 offset:224
	v_cvt_pk_bf16_f32 v2, v206, v207
	v_cvt_pk_bf16_f32 v3, v114, v115
	ds_write_b16 v147, v2 offset:2176
	ds_write_b16_d16_hi v147, v2 offset:3216
	ds_write_b16 v220, v3 offset:352
	ds_write_b16_d16_hi v220, v3 offset:480
	v_cvt_pk_bf16_f32 v4, v208, v209
	v_cvt_pk_bf16_f32 v5, v116, v117
	ds_write_b16 v147, v4 offset:4256
	ds_write_b16_d16_hi v147, v4 offset:5296
	ds_write_b16 v220, v5 offset:608
	ds_write_b16_d16_hi v220, v5 offset:736
	v_cvt_pk_bf16_f32 v6, v210, v211
	v_cvt_pk_bf16_f32 v7, v118, v119
	ds_write_b16 v147, v6 offset:6336
	ds_write_b16_d16_hi v147, v6 offset:7376
	ds_write_b16 v220, v7 offset:864
	ds_write_b16_d16_hi v220, v7 offset:992
	v_cvt_pk_bf16_f32 v8, v212, v213
	v_cvt_pk_bf16_f32 v9, v120, v121
	ds_write_b16 v147, v8 offset:8416
	ds_write_b16_d16_hi v147, v8 offset:9456
	ds_write_b16 v220, v9 offset:1120
	ds_write_b16_d16_hi v220, v9 offset:1248
	v_cvt_pk_bf16_f32 v10, v214, v215
	v_cvt_pk_bf16_f32 v11, v122, v123
	ds_write_b16 v147, v10 offset:10496
	ds_write_b16_d16_hi v147, v10 offset:11536
	ds_write_b16 v220, v11 offset:1376
	ds_write_b16_d16_hi v220, v11 offset:1504
	v_cvt_pk_bf16_f32 v12, v216, v217
	v_cvt_pk_bf16_f32 v13, v124, v125
	ds_write_b16 v147, v12 offset:12576
	ds_write_b16_d16_hi v147, v12 offset:13616
	ds_write_b16 v220, v13 offset:1632
	ds_write_b16_d16_hi v220, v13 offset:1760
	v_cvt_pk_bf16_f32 v14, v218, v219
	v_cvt_pk_bf16_f32 v15, v126, v127
	ds_write_b16 v147, v14 offset:14656
	ds_write_b16_d16_hi v147, v14 offset:15696
	ds_write_b16 v220, v15 offset:1888
	ds_write_b16_d16_hi v220, v15 offset:2016
	ds_read_b128 v[64:67], v221
	ds_read_b128 v[68:71], v222
	ds_read_b128 v[72:75], v221 offset:8320
	ds_read_b128 v[76:79], v222 offset:1024
	ds_read_b128 v[80:83], v221 offset:16640
	ds_read_b128 v[84:87], v222 offset:2048
	ds_read_b128 v[88:91], v221 offset:24960
	ds_read_b128 v[92:95], v222 offset:3072
	ds_read_b128 v[96:99], v221 offset:33280
	ds_read_b128 v[100:103], v222 offset:4096
	ds_read_b128 v[104:107], v221 offset:41600
	ds_read_b128 v[108:111], v222 offset:5120
	ds_read_b128 v[112:115], v221 offset:49920
	ds_read_b128 v[116:119], v222 offset:6144
	ds_read_b128 v[120:123], v221 offset:58240
	ds_read_b128 v[124:127], v222 offset:7168
	v_add_u32_e32 v229, 0x2000, v223
	v_add_u32_e32 v230, 0x4000, v223
	v_add_u32_e32 v231, 0x6000, v223
	v_add_u32_e32 v232, 0x8000, v223
	v_add_u32_e32 v233, 0xa000, v223
	v_add_u32_e32 v234, 0xc000, v223
	v_add_u32_e32 v235, 0xe000, v223
	s_waitcnt lgkmcnt(15)
	global_store_dwordx4 v223, v[64:67], s[10:11]
	s_waitcnt lgkmcnt(14)
	global_store_dwordx4 v223, v[68:71], s[12:13]
	s_waitcnt lgkmcnt(13)
	global_store_dwordx4 v229, v[72:75], s[10:11]
	s_waitcnt lgkmcnt(12)
	global_store_dwordx4 v229, v[76:79], s[12:13]
	s_waitcnt lgkmcnt(11)
	global_store_dwordx4 v230, v[80:83], s[10:11]
	s_waitcnt lgkmcnt(10)
	global_store_dwordx4 v230, v[84:87], s[12:13]
	s_waitcnt lgkmcnt(9)
	global_store_dwordx4 v231, v[88:91], s[10:11]
	s_waitcnt lgkmcnt(8)
	global_store_dwordx4 v231, v[92:95], s[12:13]
	s_waitcnt lgkmcnt(7)
	global_store_dwordx4 v232, v[96:99], s[10:11]
	s_waitcnt lgkmcnt(6)
	global_store_dwordx4 v232, v[100:103], s[12:13]
	s_waitcnt lgkmcnt(5)
	global_store_dwordx4 v233, v[104:107], s[10:11]
	s_waitcnt lgkmcnt(4)
	global_store_dwordx4 v233, v[108:111], s[12:13]
	s_waitcnt lgkmcnt(3)
	global_store_dwordx4 v234, v[112:115], s[10:11]
	s_waitcnt lgkmcnt(2)
	global_store_dwordx4 v234, v[116:119], s[12:13]
	s_waitcnt lgkmcnt(1)
	global_store_dwordx4 v235, v[120:123], s[10:11]
	s_waitcnt lgkmcnt(0)
	global_store_dwordx4 v235, v[124:127], s[12:13]
	s_branch .LBB0_303
